# K-loop LDS-DMA via SGPR base + 32-bit VGPR offset (no 64-bit VALU address adds in load segments), plus hand-written row pass for steps 5/8/12 (16B loads, two rows in flight, DPP wave sums, no waits be
# speedup vs baseline: 1.0134x; 1.0134x over previous
; DI int lbid() { int b = (int)blockIdx.x; asm volatile("" : "+s"(b)); return b; }
; DI int lgdim() { int g = (int)gridDim.x; asm volatile("" : "+s"(g)); return g; }
; DI f32x4 bf4(v2u raw) { return (f32x4){bf2f((unsigned short)(raw.x & 0xffffu)), bf2f((unsigned short)(raw.x >> 16)), bf2f((unsigned short)(raw.y & 0xffffu)), bf2f((unsigned short)(raw.y >> 16))}; }
; template <bool HAS_MIX, bool WRITE_H, int NR, bool SRC16, bool DST16>
; DI void row_pass(const void* xsrc, const bf16* mix, void* xdst, float* rsd, size_t rstride, int rsstride, const float* gpost, int lane) {
;     ...
;     if (HAS_MIX) {
;         float rstd[NR];
; #pragma unroll
;         for (int rr = 0; rr < NR; ++rr) { float ss = 0.f;
; #pragma unroll
;             for (int j = 0; j < 8; ++j) { const f32x4 m = bf4(mr[rr][j]); ss += (m.x * m.x + m.y * m.y) + (m.z * m.z + m.w * m.w); }
;             rstd[rr] = 1.0f / sqrtf(wave_sum(ss) * (1.0f / D) + EPS); }
; template <bool FINAL>
; DI void phase_rowpass(const Params& P, int r, const float* gpost) {
;     int tid_l = threadIdx.x; asm volatile("" : "+v"(tid_l)); const int lane = tid_l & 63, wave = tid_l >> 6;
;     const bf16* MIX = (const bf16*)(P.ws + WS_MIX); bf16* X16 = (bf16*)(P.ws + WS_X16); float* RS = (float*)(P.ws + WS_RSTD);
;     float* xo = P.out + (size_t)r * MC * D;
;     const int NGW = lgdim() * 8;
;     for (int row = lbid() * 8 + wave; row < MC; row += 2 * NGW) {
;         const size_t o = (size_t)row * D;
;         void* dst = FINAL ? (void*)(xo + o) : (void*)(X16 + o);
;         if (row + NGW < MC) row_pass<true, !FINAL, 2, true, !FINAL>(X16 + o, MIX + o, dst, RS + row, (size_t)NGW * D, NGW, gpost, lane);
;         else row_pass<true, !FINAL, 1, true, !FINAL>(X16 + o, MIX + o, dst, RS + row, 0, 0, gpost, lane);
;     }
.LBB0_159:
	s_and_b64 vcc, exec, s[4:5]
	s_cbranch_vccz .LBB0_174
	s_mov_b64 s[18:19], exec
	v_lshrrev_b32_e32 v128, 6, v152
	v_and_b32_e32 v131, 63, v152
	s_add_u32 s0, s54, 0x32700000
	v_readfirstlane_b32 s20, v128
	s_addc_u32 s1, s55, 0
	s_add_u32 s2, s54, 0x28700000
	s_addc_u32 s3, s55, 0
	s_add_u32 s4, s54, 0x10000
	s_addc_u32 s5, s55, 0
	s_cmp_eq_u32 s69, 8
	s_movk_i32 s8, 0x6000
	s_cselect_b32 s8, s8, 0x2000
	s_add_u32 s8, s35, s8
	s_addc_u32 s9, s36, 0
	s_lshl_b32 s21, s64, 3
	s_add_i32 s20, s21, s20
	s_lshl_b32 s21, s42, 3
	s_lshl_b32 s23, s21, 1
	s_add_i32 s22, s20, s21
	s_mov_b32 s24, 0x3a000000
	s_mov_b32 s25, 0x358637bd
	v_lshlrev_b32_e32 v132, 5, v131
	v_lshlrev_b32_e32 v131, 4, v131
	v_add_u32_e32 v133, 0x1000, v132
	global_load_dwordx4 v[0:3], v132, s[8:9]
	global_load_dwordx4 v[4:7], v132, s[8:9] offset:16
	global_load_dwordx4 v[8:11], v132, s[8:9] offset:2048
	global_load_dwordx4 v[12:15], v132, s[8:9] offset:2064
	global_load_dwordx4 v[16:19], v133, s[8:9]
	global_load_dwordx4 v[20:23], v133, s[8:9] offset:16
	global_load_dwordx4 v[24:27], v133, s[8:9] offset:2048
	global_load_dwordx4 v[28:31], v133, s[8:9] offset:2064
	s_lshl_b32 s26, s20, 12
	v_add_u32_e32 v134, s26, v131
	global_load_dwordx4 v[32:35], v134, s[0:1]
	global_load_dwordx4 v[36:39], v134, s[0:1] offset:1024
	global_load_dwordx4 v[40:43], v134, s[0:1] offset:2048
	global_load_dwordx4 v[44:47], v134, s[0:1] offset:3072
	global_load_dwordx4 v[48:51], v134, s[2:3] nt
	global_load_dwordx4 v[52:55], v134, s[2:3] offset:1024 nt
	global_load_dwordx4 v[56:59], v134, s[2:3] offset:2048 nt
	global_load_dwordx4 v[60:63], v134, s[2:3] offset:3072 nt
	s_lshl_b32 s26, s22, 12
	v_add_u32_e32 v135, s26, v131
	global_load_dwordx4 v[64:67], v135, s[0:1]
	global_load_dwordx4 v[68:71], v135, s[0:1] offset:1024
	global_load_dwordx4 v[72:75], v135, s[0:1] offset:2048
	global_load_dwordx4 v[76:79], v135, s[0:1] offset:3072
	global_load_dwordx4 v[80:83], v135, s[2:3] nt
	global_load_dwordx4 v[84:87], v135, s[2:3] offset:1024 nt
	global_load_dwordx4 v[88:91], v135, s[2:3] offset:2048 nt
	global_load_dwordx4 v[92:95], v135, s[2:3] offset:3072 nt
	s_waitcnt vmcnt(8)
.Lrp_top:
	s_add_i32 s6, s20, s23
	s_cmpk_lt_u32 s6, 0x4000
	s_cbranch_scc0 .Lrp_last
	s_waitcnt vmcnt(13)
	v_mov_b32_e32 v136, 0
	v_mov_b32_e32 v137, 0
	v_mov_b32_e32 v138, 0
	v_mov_b32_e32 v139, 0
	v_lshlrev_b32_e32 v96, 16, v48
	v_and_b32_e32 v97, 0xffff0000, v48
	v_lshlrev_b32_e32 v98, 16, v49
	v_and_b32_e32 v99, 0xffff0000, v49
	v_lshlrev_b32_e32 v100, 16, v50
	v_and_b32_e32 v101, 0xffff0000, v50
	v_lshlrev_b32_e32 v102, 16, v51
	v_and_b32_e32 v103, 0xffff0000, v51
	v_fmac_f32_e32 v136, v96, v96
	v_fmac_f32_e32 v137, v97, v97
	v_fmac_f32_e32 v138, v98, v98
	v_fmac_f32_e32 v139, v99, v99
	v_fmac_f32_e32 v136, v100, v100
	v_fmac_f32_e32 v137, v101, v101
	v_fmac_f32_e32 v138, v102, v102
	v_fmac_f32_e32 v139, v103, v103
	v_lshlrev_b32_e32 v104, 16, v52
	v_and_b32_e32 v105, 0xffff0000, v52
	v_lshlrev_b32_e32 v106, 16, v53
	v_and_b32_e32 v107, 0xffff0000, v53
	v_lshlrev_b32_e32 v108, 16, v54
	v_and_b32_e32 v109, 0xffff0000, v54
	v_lshlrev_b32_e32 v110, 16, v55
	v_and_b32_e32 v111, 0xffff0000, v55
	v_fmac_f32_e32 v136, v104, v104
	v_fmac_f32_e32 v137, v105, v105
	v_fmac_f32_e32 v138, v106, v106
	v_fmac_f32_e32 v139, v107, v107
	v_fmac_f32_e32 v136, v108, v108
	v_fmac_f32_e32 v137, v109, v109
	v_fmac_f32_e32 v138, v110, v110
	v_fmac_f32_e32 v139, v111, v111
	v_lshlrev_b32_e32 v112, 16, v56
	v_and_b32_e32 v113, 0xffff0000, v56
	v_lshlrev_b32_e32 v114, 16, v57
	v_and_b32_e32 v115, 0xffff0000, v57
	v_lshlrev_b32_e32 v116, 16, v58
	v_and_b32_e32 v117, 0xffff0000, v58
	v_lshlrev_b32_e32 v118, 16, v59
	v_and_b32_e32 v119, 0xffff0000, v59
	v_fmac_f32_e32 v136, v112, v112
	v_fmac_f32_e32 v137, v113, v113
	v_fmac_f32_e32 v138, v114, v114
	v_fmac_f32_e32 v139, v115, v115
	v_fmac_f32_e32 v136, v116, v116
	v_fmac_f32_e32 v137, v117, v117
	v_fmac_f32_e32 v138, v118, v118
	v_fmac_f32_e32 v139, v119, v119
	v_lshlrev_b32_e32 v120, 16, v60
	v_and_b32_e32 v121, 0xffff0000, v60
	v_lshlrev_b32_e32 v122, 16, v61
	v_and_b32_e32 v123, 0xffff0000, v61
	v_lshlrev_b32_e32 v124, 16, v62
	v_and_b32_e32 v125, 0xffff0000, v62
	v_lshlrev_b32_e32 v126, 16, v63
	v_and_b32_e32 v127, 0xffff0000, v63
	v_fmac_f32_e32 v136, v120, v120
	v_fmac_f32_e32 v137, v121, v121
	v_fmac_f32_e32 v138, v122, v122
	v_fmac_f32_e32 v139, v123, v123
	v_fmac_f32_e32 v136, v124, v124
	v_fmac_f32_e32 v137, v125, v125
	v_fmac_f32_e32 v138, v126, v126
	v_fmac_f32_e32 v139, v127, v127
	v_add_f32_e32 v136, v136, v137
	v_add_f32_e32 v138, v138, v139
	v_add_f32_e32 v136, v136, v138
	s_nop 1
	v_add_f32_dpp v136, v136, v136 quad_perm:[1,0,3,2] row_mask:0xf bank_mask:0xf
	s_nop 1
	v_add_f32_dpp v136, v136, v136 quad_perm:[2,3,0,1] row_mask:0xf bank_mask:0xf
	s_nop 1
	v_add_f32_dpp v136, v136, v136 row_half_mirror row_mask:0xf bank_mask:0xf
	s_nop 1
	v_add_f32_dpp v136, v136, v136 row_mirror row_mask:0xf bank_mask:0xf
	s_nop 1
	v_readlane_b32 s28, v136, 0
	v_readlane_b32 s29, v136, 16
	v_readlane_b32 s30, v136, 32
	v_readlane_b32 s31, v136, 48
	s_nop 1
	v_mov_b32_e32 v140, s28
	v_add_f32_e32 v140, s29, v140
	v_add_f32_e32 v140, s30, v140
	v_add_f32_e32 v140, s31, v140
	v_mov_b32_e32 v141, s25
	v_fma_f32 v140, v140, s24, v141
	v_rsq_f32_e32 v142, v140
	v_mul_f32_e32 v140, 0.5, v140
	v_mul_f32_e32 v141, v140, v142
	v_fma_f32 v141, -v141, v142, 0.5
	v_fma_f32 v142, v142, v141, v142
	v_mov_b32_e32 v136, 0
	v_mov_b32_e32 v137, 0
	v_mov_b32_e32 v138, 0
	v_mov_b32_e32 v139, 0
	v_lshlrev_b32_e32 v140, 16, v32
	v_and_b32_e32 v141, 0xffff0000, v32
	v_mul_f32_e32 v96, v96, v142
	v_mul_f32_e32 v97, v97, v142
; DI unsigned pk2(float lo, float hi) { return pg8::cvt_pk_bf16(lo, hi); }
; DI f32x4 bf4(v2u raw) { return (f32x4){bf2f((unsigned short)(raw.x & 0xffffu)), bf2f((unsigned short)(raw.x >> 16)), bf2f((unsigned short)(raw.y & 0xffffu)), bf2f((unsigned short)(raw.y >> 16))}; }
; template <bool HAS_MIX, bool WRITE_H, int NR, bool SRC16, bool DST16>
; DI void row_pass(const void* xsrc, const bf16* mix, void* xdst, float* rsd, size_t rstride, int rsstride, const float* gpost, int lane) {
;     ...
; #pragma unroll
;         for (int j = 0; j < 8; ++j) { const f32x4 g = ((const f32x4*)gpost)[lane + 64 * j];
; #pragma unroll
;             for (int rr = 0; rr < NR; ++rr) { v[rr][j] = v[rr][j] + bf4(mr[rr][j]) * rstd[rr] * g;
;                 if (DST16) { v2u w; w.x = pk2(v[rr][j].x, v[rr][j].y); w.y = pk2(v[rr][j].z, v[rr][j].w); ((v2u*)((bf16*)xdst + rr * rstride))[lane + 64 * j] = w; }
;                 else __builtin_nontemporal_store(v[rr][j], (f32x4*)((float*)xdst + rr * rstride) + lane + 64 * j); } }
;     }
;     if (WRITE_H) {
; #pragma unroll
;         for (int rr = 0; rr < NR; ++rr) { float ss = 0.f;
; #pragma unroll
;             for (int j = 0; j < 8; ++j) ss += (v[rr][j].x * v[rr][j].x + v[rr][j].y * v[rr][j].y) + (v[rr][j].z * v[rr][j].z + v[rr][j].w * v[rr][j].w);
;             const float rstd = 1.0f / sqrtf(wave_sum(ss) * (1.0f / D) + EPS);
;             if (lane == 0) rsd[rr * rsstride] = rstd; }
	v_fma_f32 v96, v96, v0, v140
	v_fma_f32 v97, v97, v1, v141
	v_fmac_f32_e32 v136, v96, v96
	v_fmac_f32_e32 v137, v97, v97
	v_cvt_pk_bf16_f32 v32, v96, v97
	v_lshlrev_b32_e32 v132, 16, v33
	v_and_b32_e32 v133, 0xffff0000, v33
	v_mul_f32_e32 v98, v98, v142
	v_mul_f32_e32 v99, v99, v142
	v_fma_f32 v98, v98, v2, v132
	v_fma_f32 v99, v99, v3, v133
	v_fmac_f32_e32 v138, v98, v98
	v_fmac_f32_e32 v139, v99, v99
	v_cvt_pk_bf16_f32 v33, v98, v99
	v_lshlrev_b32_e32 v140, 16, v34
	v_and_b32_e32 v141, 0xffff0000, v34
	v_mul_f32_e32 v100, v100, v142
	v_mul_f32_e32 v101, v101, v142
	v_fma_f32 v100, v100, v4, v140
	v_fma_f32 v101, v101, v5, v141
	v_fmac_f32_e32 v136, v100, v100
	v_fmac_f32_e32 v137, v101, v101
	v_cvt_pk_bf16_f32 v34, v100, v101
	v_lshlrev_b32_e32 v132, 16, v35
	v_and_b32_e32 v133, 0xffff0000, v35
	v_mul_f32_e32 v102, v102, v142
	v_mul_f32_e32 v103, v103, v142
	v_fma_f32 v102, v102, v6, v132
	v_fma_f32 v103, v103, v7, v133
	v_fmac_f32_e32 v138, v102, v102
	v_fmac_f32_e32 v139, v103, v103
	v_cvt_pk_bf16_f32 v35, v102, v103
	global_store_dwordx4 v134, v[32:35], s[0:1]
	v_lshlrev_b32_e32 v140, 16, v36
	v_and_b32_e32 v141, 0xffff0000, v36
	v_mul_f32_e32 v104, v104, v142
	v_mul_f32_e32 v105, v105, v142
	v_fma_f32 v104, v104, v8, v140
	v_fma_f32 v105, v105, v9, v141
	v_fmac_f32_e32 v136, v104, v104
	v_fmac_f32_e32 v137, v105, v105
	v_cvt_pk_bf16_f32 v36, v104, v105
	v_lshlrev_b32_e32 v132, 16, v37
	v_and_b32_e32 v133, 0xffff0000, v37
	v_mul_f32_e32 v106, v106, v142
	v_mul_f32_e32 v107, v107, v142
	v_fma_f32 v106, v106, v10, v132
	v_fma_f32 v107, v107, v11, v133
	v_fmac_f32_e32 v138, v106, v106
	v_fmac_f32_e32 v139, v107, v107
	v_cvt_pk_bf16_f32 v37, v106, v107
	v_lshlrev_b32_e32 v140, 16, v38
	v_and_b32_e32 v141, 0xffff0000, v38
	v_mul_f32_e32 v108, v108, v142
	v_mul_f32_e32 v109, v109, v142
	v_fma_f32 v108, v108, v12, v140
	v_fma_f32 v109, v109, v13, v141
	v_fmac_f32_e32 v136, v108, v108
	v_fmac_f32_e32 v137, v109, v109
	v_cvt_pk_bf16_f32 v38, v108, v109
	v_lshlrev_b32_e32 v132, 16, v39
	v_and_b32_e32 v133, 0xffff0000, v39
	v_mul_f32_e32 v110, v110, v142
	v_mul_f32_e32 v111, v111, v142
	v_fma_f32 v110, v110, v14, v132
	v_fma_f32 v111, v111, v15, v133
	v_fmac_f32_e32 v138, v110, v110
	v_fmac_f32_e32 v139, v111, v111
	v_cvt_pk_bf16_f32 v39, v110, v111
	global_store_dwordx4 v134, v[36:39], s[0:1] offset:1024
	v_lshlrev_b32_e32 v140, 16, v40
	v_and_b32_e32 v141, 0xffff0000, v40
	v_mul_f32_e32 v112, v112, v142
	v_mul_f32_e32 v113, v113, v142
	v_fma_f32 v112, v112, v16, v140
	v_fma_f32 v113, v113, v17, v141
	v_fmac_f32_e32 v136, v112, v112
	v_fmac_f32_e32 v137, v113, v113
	v_cvt_pk_bf16_f32 v40, v112, v113
	v_lshlrev_b32_e32 v132, 16, v41
	v_and_b32_e32 v133, 0xffff0000, v41
	v_mul_f32_e32 v114, v114, v142
	v_mul_f32_e32 v115, v115, v142
	v_fma_f32 v114, v114, v18, v132
	v_fma_f32 v115, v115, v19, v133
	v_fmac_f32_e32 v138, v114, v114
	v_fmac_f32_e32 v139, v115, v115
	v_cvt_pk_bf16_f32 v41, v114, v115
	v_lshlrev_b32_e32 v140, 16, v42
	v_and_b32_e32 v141, 0xffff0000, v42
	v_mul_f32_e32 v116, v116, v142
	v_mul_f32_e32 v117, v117, v142
	v_fma_f32 v116, v116, v20, v140
	v_fma_f32 v117, v117, v21, v141
	v_fmac_f32_e32 v136, v116, v116
	v_fmac_f32_e32 v137, v117, v117
	v_cvt_pk_bf16_f32 v42, v116, v117
	v_lshlrev_b32_e32 v132, 16, v43
	v_and_b32_e32 v133, 0xffff0000, v43
	v_mul_f32_e32 v118, v118, v142
	v_mul_f32_e32 v119, v119, v142
	v_fma_f32 v118, v118, v22, v132
	v_fma_f32 v119, v119, v23, v133
	v_fmac_f32_e32 v138, v118, v118
	v_fmac_f32_e32 v139, v119, v119
	v_cvt_pk_bf16_f32 v43, v118, v119
	global_store_dwordx4 v134, v[40:43], s[0:1] offset:2048
	v_lshlrev_b32_e32 v140, 16, v44
	v_and_b32_e32 v141, 0xffff0000, v44
	v_mul_f32_e32 v120, v120, v142
	v_mul_f32_e32 v121, v121, v142
	v_fma_f32 v120, v120, v24, v140
	v_fma_f32 v121, v121, v25, v141
	v_fmac_f32_e32 v136, v120, v120
	v_fmac_f32_e32 v137, v121, v121
	v_cvt_pk_bf16_f32 v44, v120, v121
	v_lshlrev_b32_e32 v132, 16, v45
	v_and_b32_e32 v133, 0xffff0000, v45
	v_mul_f32_e32 v122, v122, v142
	v_mul_f32_e32 v123, v123, v142
	v_fma_f32 v122, v122, v26, v132
	v_fma_f32 v123, v123, v27, v133
	v_fmac_f32_e32 v138, v122, v122
	v_fmac_f32_e32 v139, v123, v123
	v_cvt_pk_bf16_f32 v45, v122, v123
	v_lshlrev_b32_e32 v140, 16, v46
	v_and_b32_e32 v141, 0xffff0000, v46
	v_mul_f32_e32 v124, v124, v142
	v_mul_f32_e32 v125, v125, v142
	v_fma_f32 v124, v124, v28, v140
	v_fma_f32 v125, v125, v29, v141
	v_fmac_f32_e32 v136, v124, v124
	v_fmac_f32_e32 v137, v125, v125
	v_cvt_pk_bf16_f32 v46, v124, v125
	v_lshlrev_b32_e32 v132, 16, v47
	v_and_b32_e32 v133, 0xffff0000, v47
	v_mul_f32_e32 v126, v126, v142
	v_mul_f32_e32 v127, v127, v142
	v_fma_f32 v126, v126, v30, v132
	v_fma_f32 v127, v127, v31, v133
	v_fmac_f32_e32 v138, v126, v126
	v_fmac_f32_e32 v139, v127, v127
	v_cvt_pk_bf16_f32 v47, v126, v127
	global_store_dwordx4 v134, v[44:47], s[0:1] offset:3072
	v_add_f32_e32 v136, v136, v137
	v_add_f32_e32 v138, v138, v139
	v_add_f32_e32 v136, v136, v138
	s_nop 1
	v_add_f32_dpp v136, v136, v136 quad_perm:[1,0,3,2] row_mask:0xf bank_mask:0xf
	s_nop 1
	v_add_f32_dpp v136, v136, v136 quad_perm:[2,3,0,1] row_mask:0xf bank_mask:0xf
	s_nop 1
	v_add_f32_dpp v136, v136, v136 row_half_mirror row_mask:0xf bank_mask:0xf
	s_nop 1
	v_add_f32_dpp v136, v136, v136 row_mirror row_mask:0xf bank_mask:0xf
	s_nop 1
	v_readlane_b32 s28, v136, 0
	v_readlane_b32 s29, v136, 16
	v_readlane_b32 s30, v136, 32
	v_readlane_b32 s31, v136, 48
	s_nop 1
	v_mov_b32_e32 v140, s28
	v_add_f32_e32 v140, s29, v140
	v_add_f32_e32 v140, s30, v140
	v_add_f32_e32 v140, s31, v140
	v_mov_b32_e32 v141, s25
	v_fma_f32 v140, v140, s24, v141
	v_rsq_f32_e32 v128, v140
	v_mul_f32_e32 v140, 0.5, v140
	v_mul_f32_e32 v141, v140, v128
	v_fma_f32 v141, -v141, v128, 0.5
	v_fma_f32 v128, v128, v141, v128
	s_lshl_b32 s26, s20, 2
	s_add_u32 s26, s4, s26
	s_addc_u32 s27, s5, 0
	v_mov_b32_e32 v140, 0
	s_mov_b64 exec, 1
	global_store_dword v140, v128, s[26:27]
	s_mov_b64 exec, -1
	s_add_i32 s20, s20, s23
	s_lshl_b32 s26, s20, 12
	v_add_u32_e32 v134, s26, v131
	global_load_dwordx4 v[32:35], v134, s[0:1]
	global_load_dwordx4 v[36:39], v134, s[0:1] offset:1024
	global_load_dwordx4 v[40:43], v134, s[0:1] offset:2048
	global_load_dwordx4 v[44:47], v134, s[0:1] offset:3072
	global_load_dwordx4 v[48:51], v134, s[2:3] nt
	global_load_dwordx4 v[52:55], v134, s[2:3] offset:1024 nt
	global_load_dwordx4 v[56:59], v134, s[2:3] offset:2048 nt
	global_load_dwordx4 v[60:63], v134, s[2:3] offset:3072 nt
	s_waitcnt vmcnt(13)
; DI unsigned pk2(float lo, float hi) { return pg8::cvt_pk_bf16(lo, hi); }
; DI f32x4 bf4(v2u raw) { return (f32x4){bf2f((unsigned short)(raw.x & 0xffffu)), bf2f((unsigned short)(raw.x >> 16)), bf2f((unsigned short)(raw.y & 0xffffu)), bf2f((unsigned short)(raw.y >> 16))}; }
; template <bool HAS_MIX, bool WRITE_H, int NR, bool SRC16, bool DST16>
; DI void row_pass(const void* xsrc, const bf16* mix, void* xdst, float* rsd, size_t rstride, int rsstride, const float* gpost, int lane) {
;     ...
;     if (HAS_MIX) {
;         float rstd[NR];
; #pragma unroll
;         for (int rr = 0; rr < NR; ++rr) { float ss = 0.f;
; #pragma unroll
;             for (int j = 0; j < 8; ++j) { const f32x4 m = bf4(mr[rr][j]); ss += (m.x * m.x + m.y * m.y) + (m.z * m.z + m.w * m.w); }
;             rstd[rr] = 1.0f / sqrtf(wave_sum(ss) * (1.0f / D) + EPS); }
; #pragma unroll
;         for (int j = 0; j < 8; ++j) { const f32x4 g = ((const f32x4*)gpost)[lane + 64 * j];
; #pragma unroll
;             for (int rr = 0; rr < NR; ++rr) { v[rr][j] = v[rr][j] + bf4(mr[rr][j]) * rstd[rr] * g;
;                 if (DST16) { v2u w; w.x = pk2(v[rr][j].x, v[rr][j].y); w.y = pk2(v[rr][j].z, v[rr][j].w); ((v2u*)((bf16*)xdst + rr * rstride))[lane + 64 * j] = w; }
;                 else __builtin_nontemporal_store(v[rr][j], (f32x4*)((float*)xdst + rr * rstride) + lane + 64 * j); } }
	v_mov_b32_e32 v136, 0
	v_mov_b32_e32 v137, 0
	v_mov_b32_e32 v138, 0
	v_mov_b32_e32 v139, 0
	v_lshlrev_b32_e32 v96, 16, v80
	v_and_b32_e32 v97, 0xffff0000, v80
	v_lshlrev_b32_e32 v98, 16, v81
	v_and_b32_e32 v99, 0xffff0000, v81
	v_lshlrev_b32_e32 v100, 16, v82
	v_and_b32_e32 v101, 0xffff0000, v82
	v_lshlrev_b32_e32 v102, 16, v83
	v_and_b32_e32 v103, 0xffff0000, v83
	v_fmac_f32_e32 v136, v96, v96
	v_fmac_f32_e32 v137, v97, v97
	v_fmac_f32_e32 v138, v98, v98
	v_fmac_f32_e32 v139, v99, v99
	v_fmac_f32_e32 v136, v100, v100
	v_fmac_f32_e32 v137, v101, v101
	v_fmac_f32_e32 v138, v102, v102
	v_fmac_f32_e32 v139, v103, v103
	v_lshlrev_b32_e32 v104, 16, v84
	v_and_b32_e32 v105, 0xffff0000, v84
	v_lshlrev_b32_e32 v106, 16, v85
	v_and_b32_e32 v107, 0xffff0000, v85
	v_lshlrev_b32_e32 v108, 16, v86
	v_and_b32_e32 v109, 0xffff0000, v86
	v_lshlrev_b32_e32 v110, 16, v87
	v_and_b32_e32 v111, 0xffff0000, v87
	v_fmac_f32_e32 v136, v104, v104
	v_fmac_f32_e32 v137, v105, v105
	v_fmac_f32_e32 v138, v106, v106
	v_fmac_f32_e32 v139, v107, v107
	v_fmac_f32_e32 v136, v108, v108
	v_fmac_f32_e32 v137, v109, v109
	v_fmac_f32_e32 v138, v110, v110
	v_fmac_f32_e32 v139, v111, v111
	v_lshlrev_b32_e32 v112, 16, v88
	v_and_b32_e32 v113, 0xffff0000, v88
	v_lshlrev_b32_e32 v114, 16, v89
	v_and_b32_e32 v115, 0xffff0000, v89
	v_lshlrev_b32_e32 v116, 16, v90
	v_and_b32_e32 v117, 0xffff0000, v90
	v_lshlrev_b32_e32 v118, 16, v91
	v_and_b32_e32 v119, 0xffff0000, v91
	v_fmac_f32_e32 v136, v112, v112
	v_fmac_f32_e32 v137, v113, v113
	v_fmac_f32_e32 v138, v114, v114
	v_fmac_f32_e32 v139, v115, v115
	v_fmac_f32_e32 v136, v116, v116
	v_fmac_f32_e32 v137, v117, v117
	v_fmac_f32_e32 v138, v118, v118
	v_fmac_f32_e32 v139, v119, v119
	v_lshlrev_b32_e32 v120, 16, v92
	v_and_b32_e32 v121, 0xffff0000, v92
	v_lshlrev_b32_e32 v122, 16, v93
	v_and_b32_e32 v123, 0xffff0000, v93
	v_lshlrev_b32_e32 v124, 16, v94
	v_and_b32_e32 v125, 0xffff0000, v94
	v_lshlrev_b32_e32 v126, 16, v95
	v_and_b32_e32 v127, 0xffff0000, v95
	v_fmac_f32_e32 v136, v120, v120
	v_fmac_f32_e32 v137, v121, v121
	v_fmac_f32_e32 v138, v122, v122
	v_fmac_f32_e32 v139, v123, v123
	v_fmac_f32_e32 v136, v124, v124
	v_fmac_f32_e32 v137, v125, v125
	v_fmac_f32_e32 v138, v126, v126
	v_fmac_f32_e32 v139, v127, v127
	v_add_f32_e32 v136, v136, v137
	v_add_f32_e32 v138, v138, v139
	v_add_f32_e32 v136, v136, v138
	s_nop 1
	v_add_f32_dpp v136, v136, v136 quad_perm:[1,0,3,2] row_mask:0xf bank_mask:0xf
	s_nop 1
	v_add_f32_dpp v136, v136, v136 quad_perm:[2,3,0,1] row_mask:0xf bank_mask:0xf
	s_nop 1
	v_add_f32_dpp v136, v136, v136 row_half_mirror row_mask:0xf bank_mask:0xf
	s_nop 1
	v_add_f32_dpp v136, v136, v136 row_mirror row_mask:0xf bank_mask:0xf
	s_nop 1
	v_readlane_b32 s28, v136, 0
	v_readlane_b32 s29, v136, 16
	v_readlane_b32 s30, v136, 32
	v_readlane_b32 s31, v136, 48
	s_nop 1
	v_mov_b32_e32 v140, s28
	v_add_f32_e32 v140, s29, v140
	v_add_f32_e32 v140, s30, v140
	v_add_f32_e32 v140, s31, v140
	v_mov_b32_e32 v141, s25
	v_fma_f32 v140, v140, s24, v141
	v_rsq_f32_e32 v142, v140
	v_mul_f32_e32 v140, 0.5, v140
	v_mul_f32_e32 v141, v140, v142
	v_fma_f32 v141, -v141, v142, 0.5
	v_fma_f32 v142, v142, v141, v142
	v_mov_b32_e32 v136, 0
	v_mov_b32_e32 v137, 0
	v_mov_b32_e32 v138, 0
	v_mov_b32_e32 v139, 0
	v_lshlrev_b32_e32 v140, 16, v64
	v_and_b32_e32 v141, 0xffff0000, v64
	v_mul_f32_e32 v96, v96, v142
	v_mul_f32_e32 v97, v97, v142
	v_fma_f32 v96, v96, v0, v140
	v_fma_f32 v97, v97, v1, v141
	v_fmac_f32_e32 v136, v96, v96
	v_fmac_f32_e32 v137, v97, v97
	v_cvt_pk_bf16_f32 v64, v96, v97
	v_lshlrev_b32_e32 v132, 16, v65
	v_and_b32_e32 v133, 0xffff0000, v65
	v_mul_f32_e32 v98, v98, v142
	v_mul_f32_e32 v99, v99, v142
	v_fma_f32 v98, v98, v2, v132
	v_fma_f32 v99, v99, v3, v133
	v_fmac_f32_e32 v138, v98, v98
	v_fmac_f32_e32 v139, v99, v99
	v_cvt_pk_bf16_f32 v65, v98, v99
	v_lshlrev_b32_e32 v140, 16, v66
	v_and_b32_e32 v141, 0xffff0000, v66
	v_mul_f32_e32 v100, v100, v142
	v_mul_f32_e32 v101, v101, v142
	v_fma_f32 v100, v100, v4, v140
	v_fma_f32 v101, v101, v5, v141
	v_fmac_f32_e32 v136, v100, v100
	v_fmac_f32_e32 v137, v101, v101
	v_cvt_pk_bf16_f32 v66, v100, v101
	v_lshlrev_b32_e32 v132, 16, v67
	v_and_b32_e32 v133, 0xffff0000, v67
	v_mul_f32_e32 v102, v102, v142
	v_mul_f32_e32 v103, v103, v142
	v_fma_f32 v102, v102, v6, v132
	v_fma_f32 v103, v103, v7, v133
	v_fmac_f32_e32 v138, v102, v102
	v_fmac_f32_e32 v139, v103, v103
	v_cvt_pk_bf16_f32 v67, v102, v103
	global_store_dwordx4 v135, v[64:67], s[0:1]
	v_lshlrev_b32_e32 v140, 16, v68
	v_and_b32_e32 v141, 0xffff0000, v68
	v_mul_f32_e32 v104, v104, v142
	v_mul_f32_e32 v105, v105, v142
	v_fma_f32 v104, v104, v8, v140
	v_fma_f32 v105, v105, v9, v141
	v_fmac_f32_e32 v136, v104, v104
	v_fmac_f32_e32 v137, v105, v105
	v_cvt_pk_bf16_f32 v68, v104, v105
	v_lshlrev_b32_e32 v132, 16, v69
	v_and_b32_e32 v133, 0xffff0000, v69
	v_mul_f32_e32 v106, v106, v142
	v_mul_f32_e32 v107, v107, v142
	v_fma_f32 v106, v106, v10, v132
	v_fma_f32 v107, v107, v11, v133
	v_fmac_f32_e32 v138, v106, v106
	v_fmac_f32_e32 v139, v107, v107
	v_cvt_pk_bf16_f32 v69, v106, v107
	v_lshlrev_b32_e32 v140, 16, v70
	v_and_b32_e32 v141, 0xffff0000, v70
	v_mul_f32_e32 v108, v108, v142
	v_mul_f32_e32 v109, v109, v142
	v_fma_f32 v108, v108, v12, v140
	v_fma_f32 v109, v109, v13, v141
	v_fmac_f32_e32 v136, v108, v108
	v_fmac_f32_e32 v137, v109, v109
	v_cvt_pk_bf16_f32 v70, v108, v109
	v_lshlrev_b32_e32 v132, 16, v71
	v_and_b32_e32 v133, 0xffff0000, v71
	v_mul_f32_e32 v110, v110, v142
	v_mul_f32_e32 v111, v111, v142
	v_fma_f32 v110, v110, v14, v132
	v_fma_f32 v111, v111, v15, v133
	v_fmac_f32_e32 v138, v110, v110
	v_fmac_f32_e32 v139, v111, v111
; DI unsigned pk2(float lo, float hi) { return pg8::cvt_pk_bf16(lo, hi); }
; DI f32x4 bf4(v2u raw) { return (f32x4){bf2f((unsigned short)(raw.x & 0xffffu)), bf2f((unsigned short)(raw.x >> 16)), bf2f((unsigned short)(raw.y & 0xffffu)), bf2f((unsigned short)(raw.y >> 16))}; }
; template <bool HAS_MIX, bool WRITE_H, int NR, bool SRC16, bool DST16>
; DI void row_pass(const void* xsrc, const bf16* mix, void* xdst, float* rsd, size_t rstride, int rsstride, const float* gpost, int lane) {
;     ...
; #pragma unroll
;         for (int j = 0; j < 8; ++j) { const f32x4 g = ((const f32x4*)gpost)[lane + 64 * j];
; #pragma unroll
;             for (int rr = 0; rr < NR; ++rr) { v[rr][j] = v[rr][j] + bf4(mr[rr][j]) * rstd[rr] * g;
;                 if (DST16) { v2u w; w.x = pk2(v[rr][j].x, v[rr][j].y); w.y = pk2(v[rr][j].z, v[rr][j].w); ((v2u*)((bf16*)xdst + rr * rstride))[lane + 64 * j] = w; }
;                 else __builtin_nontemporal_store(v[rr][j], (f32x4*)((float*)xdst + rr * rstride) + lane + 64 * j); } }
;     }
;     if (WRITE_H) {
; #pragma unroll
;         for (int rr = 0; rr < NR; ++rr) { float ss = 0.f;
; #pragma unroll
;             for (int j = 0; j < 8; ++j) ss += (v[rr][j].x * v[rr][j].x + v[rr][j].y * v[rr][j].y) + (v[rr][j].z * v[rr][j].z + v[rr][j].w * v[rr][j].w);
;             const float rstd = 1.0f / sqrtf(wave_sum(ss) * (1.0f / D) + EPS);
;             if (lane == 0) rsd[rr * rsstride] = rstd; }
	v_cvt_pk_bf16_f32 v71, v110, v111
	global_store_dwordx4 v135, v[68:71], s[0:1] offset:1024
	v_lshlrev_b32_e32 v140, 16, v72
	v_and_b32_e32 v141, 0xffff0000, v72
	v_mul_f32_e32 v112, v112, v142
	v_mul_f32_e32 v113, v113, v142
	v_fma_f32 v112, v112, v16, v140
	v_fma_f32 v113, v113, v17, v141
	v_fmac_f32_e32 v136, v112, v112
	v_fmac_f32_e32 v137, v113, v113
	v_cvt_pk_bf16_f32 v72, v112, v113
	v_lshlrev_b32_e32 v132, 16, v73
	v_and_b32_e32 v133, 0xffff0000, v73
	v_mul_f32_e32 v114, v114, v142
	v_mul_f32_e32 v115, v115, v142
	v_fma_f32 v114, v114, v18, v132
	v_fma_f32 v115, v115, v19, v133
	v_fmac_f32_e32 v138, v114, v114
	v_fmac_f32_e32 v139, v115, v115
	v_cvt_pk_bf16_f32 v73, v114, v115
	v_lshlrev_b32_e32 v140, 16, v74
	v_and_b32_e32 v141, 0xffff0000, v74
	v_mul_f32_e32 v116, v116, v142
	v_mul_f32_e32 v117, v117, v142
	v_fma_f32 v116, v116, v20, v140
	v_fma_f32 v117, v117, v21, v141
	v_fmac_f32_e32 v136, v116, v116
	v_fmac_f32_e32 v137, v117, v117
	v_cvt_pk_bf16_f32 v74, v116, v117
	v_lshlrev_b32_e32 v132, 16, v75
	v_and_b32_e32 v133, 0xffff0000, v75
	v_mul_f32_e32 v118, v118, v142
	v_mul_f32_e32 v119, v119, v142
	v_fma_f32 v118, v118, v22, v132
	v_fma_f32 v119, v119, v23, v133
	v_fmac_f32_e32 v138, v118, v118
	v_fmac_f32_e32 v139, v119, v119
	v_cvt_pk_bf16_f32 v75, v118, v119
	global_store_dwordx4 v135, v[72:75], s[0:1] offset:2048
	v_lshlrev_b32_e32 v140, 16, v76
	v_and_b32_e32 v141, 0xffff0000, v76
	v_mul_f32_e32 v120, v120, v142
	v_mul_f32_e32 v121, v121, v142
	v_fma_f32 v120, v120, v24, v140
	v_fma_f32 v121, v121, v25, v141
	v_fmac_f32_e32 v136, v120, v120
	v_fmac_f32_e32 v137, v121, v121
	v_cvt_pk_bf16_f32 v76, v120, v121
	v_lshlrev_b32_e32 v132, 16, v77
	v_and_b32_e32 v133, 0xffff0000, v77
	v_mul_f32_e32 v122, v122, v142
	v_mul_f32_e32 v123, v123, v142
	v_fma_f32 v122, v122, v26, v132
	v_fma_f32 v123, v123, v27, v133
	v_fmac_f32_e32 v138, v122, v122
	v_fmac_f32_e32 v139, v123, v123
	v_cvt_pk_bf16_f32 v77, v122, v123
	v_lshlrev_b32_e32 v140, 16, v78
	v_and_b32_e32 v141, 0xffff0000, v78
	v_mul_f32_e32 v124, v124, v142
	v_mul_f32_e32 v125, v125, v142
	v_fma_f32 v124, v124, v28, v140
	v_fma_f32 v125, v125, v29, v141
	v_fmac_f32_e32 v136, v124, v124
	v_fmac_f32_e32 v137, v125, v125
	v_cvt_pk_bf16_f32 v78, v124, v125
	v_lshlrev_b32_e32 v132, 16, v79
	v_and_b32_e32 v133, 0xffff0000, v79
	v_mul_f32_e32 v126, v126, v142
	v_mul_f32_e32 v127, v127, v142
	v_fma_f32 v126, v126, v30, v132
	v_fma_f32 v127, v127, v31, v133
	v_fmac_f32_e32 v138, v126, v126
	v_fmac_f32_e32 v139, v127, v127
	v_cvt_pk_bf16_f32 v79, v126, v127
	global_store_dwordx4 v135, v[76:79], s[0:1] offset:3072
	v_add_f32_e32 v136, v136, v137
	v_add_f32_e32 v138, v138, v139
	v_add_f32_e32 v136, v136, v138
	s_nop 1
	v_add_f32_dpp v136, v136, v136 quad_perm:[1,0,3,2] row_mask:0xf bank_mask:0xf
	s_nop 1
	v_add_f32_dpp v136, v136, v136 quad_perm:[2,3,0,1] row_mask:0xf bank_mask:0xf
	s_nop 1
	v_add_f32_dpp v136, v136, v136 row_half_mirror row_mask:0xf bank_mask:0xf
	s_nop 1
	v_add_f32_dpp v136, v136, v136 row_mirror row_mask:0xf bank_mask:0xf
	s_nop 1
	v_readlane_b32 s28, v136, 0
	v_readlane_b32 s29, v136, 16
	v_readlane_b32 s30, v136, 32
	v_readlane_b32 s31, v136, 48
	s_nop 1
	v_mov_b32_e32 v140, s28
	v_add_f32_e32 v140, s29, v140
	v_add_f32_e32 v140, s30, v140
	v_add_f32_e32 v140, s31, v140
	v_mov_b32_e32 v141, s25
	v_fma_f32 v140, v140, s24, v141
	v_rsq_f32_e32 v128, v140
	v_mul_f32_e32 v140, 0.5, v140
	v_mul_f32_e32 v141, v140, v128
	v_fma_f32 v141, -v141, v128, 0.5
	v_fma_f32 v128, v128, v141, v128
	s_lshl_b32 s26, s22, 2
	s_add_u32 s26, s4, s26
	s_addc_u32 s27, s5, 0
	v_mov_b32_e32 v140, 0
	s_mov_b64 exec, 1
	global_store_dword v140, v128, s[26:27]
	s_mov_b64 exec, -1
	s_add_i32 s22, s22, s23
	s_lshl_b32 s26, s22, 12
	v_add_u32_e32 v135, s26, v131
	global_load_dwordx4 v[64:67], v135, s[0:1]
	global_load_dwordx4 v[68:71], v135, s[0:1] offset:1024
	global_load_dwordx4 v[72:75], v135, s[0:1] offset:2048
	global_load_dwordx4 v[76:79], v135, s[0:1] offset:3072
	global_load_dwordx4 v[80:83], v135, s[2:3] nt
	global_load_dwordx4 v[84:87], v135, s[2:3] offset:1024 nt
	global_load_dwordx4 v[88:91], v135, s[2:3] offset:2048 nt
	global_load_dwordx4 v[92:95], v135, s[2:3] offset:3072 nt
	s_branch .Lrp_top
.Lrp_last:
	s_waitcnt vmcnt(13)
; DI unsigned pk2(float lo, float hi) { return pg8::cvt_pk_bf16(lo, hi); }
; DI f32x4 bf4(v2u raw) { return (f32x4){bf2f((unsigned short)(raw.x & 0xffffu)), bf2f((unsigned short)(raw.x >> 16)), bf2f((unsigned short)(raw.y & 0xffffu)), bf2f((unsigned short)(raw.y >> 16))}; }
; template <bool HAS_MIX, bool WRITE_H, int NR, bool SRC16, bool DST16>
; DI void row_pass(const void* xsrc, const bf16* mix, void* xdst, float* rsd, size_t rstride, int rsstride, const float* gpost, int lane) {
;     ...
;     if (HAS_MIX) {
;         float rstd[NR];
; #pragma unroll
;         for (int rr = 0; rr < NR; ++rr) { float ss = 0.f;
; #pragma unroll
;             for (int j = 0; j < 8; ++j) { const f32x4 m = bf4(mr[rr][j]); ss += (m.x * m.x + m.y * m.y) + (m.z * m.z + m.w * m.w); }
;             rstd[rr] = 1.0f / sqrtf(wave_sum(ss) * (1.0f / D) + EPS); }
; #pragma unroll
;         for (int j = 0; j < 8; ++j) { const f32x4 g = ((const f32x4*)gpost)[lane + 64 * j];
; #pragma unroll
;             for (int rr = 0; rr < NR; ++rr) { v[rr][j] = v[rr][j] + bf4(mr[rr][j]) * rstd[rr] * g;
;                 if (DST16) { v2u w; w.x = pk2(v[rr][j].x, v[rr][j].y); w.y = pk2(v[rr][j].z, v[rr][j].w); ((v2u*)((bf16*)xdst + rr * rstride))[lane + 64 * j] = w; }
;                 else __builtin_nontemporal_store(v[rr][j], (f32x4*)((float*)xdst + rr * rstride) + lane + 64 * j); } }
	v_mov_b32_e32 v136, 0
	v_mov_b32_e32 v137, 0
	v_mov_b32_e32 v138, 0
	v_mov_b32_e32 v139, 0
	v_lshlrev_b32_e32 v96, 16, v48
	v_and_b32_e32 v97, 0xffff0000, v48
	v_lshlrev_b32_e32 v98, 16, v49
	v_and_b32_e32 v99, 0xffff0000, v49
	v_lshlrev_b32_e32 v100, 16, v50
	v_and_b32_e32 v101, 0xffff0000, v50
	v_lshlrev_b32_e32 v102, 16, v51
	v_and_b32_e32 v103, 0xffff0000, v51
	v_fmac_f32_e32 v136, v96, v96
	v_fmac_f32_e32 v137, v97, v97
	v_fmac_f32_e32 v138, v98, v98
	v_fmac_f32_e32 v139, v99, v99
	v_fmac_f32_e32 v136, v100, v100
	v_fmac_f32_e32 v137, v101, v101
	v_fmac_f32_e32 v138, v102, v102
	v_fmac_f32_e32 v139, v103, v103
	v_lshlrev_b32_e32 v104, 16, v52
	v_and_b32_e32 v105, 0xffff0000, v52
	v_lshlrev_b32_e32 v106, 16, v53
	v_and_b32_e32 v107, 0xffff0000, v53
	v_lshlrev_b32_e32 v108, 16, v54
	v_and_b32_e32 v109, 0xffff0000, v54
	v_lshlrev_b32_e32 v110, 16, v55
	v_and_b32_e32 v111, 0xffff0000, v55
	v_fmac_f32_e32 v136, v104, v104
	v_fmac_f32_e32 v137, v105, v105
	v_fmac_f32_e32 v138, v106, v106
	v_fmac_f32_e32 v139, v107, v107
	v_fmac_f32_e32 v136, v108, v108
	v_fmac_f32_e32 v137, v109, v109
	v_fmac_f32_e32 v138, v110, v110
	v_fmac_f32_e32 v139, v111, v111
	v_lshlrev_b32_e32 v112, 16, v56
	v_and_b32_e32 v113, 0xffff0000, v56
	v_lshlrev_b32_e32 v114, 16, v57
	v_and_b32_e32 v115, 0xffff0000, v57
	v_lshlrev_b32_e32 v116, 16, v58
	v_and_b32_e32 v117, 0xffff0000, v58
	v_lshlrev_b32_e32 v118, 16, v59
	v_and_b32_e32 v119, 0xffff0000, v59
	v_fmac_f32_e32 v136, v112, v112
	v_fmac_f32_e32 v137, v113, v113
	v_fmac_f32_e32 v138, v114, v114
	v_fmac_f32_e32 v139, v115, v115
	v_fmac_f32_e32 v136, v116, v116
	v_fmac_f32_e32 v137, v117, v117
	v_fmac_f32_e32 v138, v118, v118
	v_fmac_f32_e32 v139, v119, v119
	v_lshlrev_b32_e32 v120, 16, v60
	v_and_b32_e32 v121, 0xffff0000, v60
	v_lshlrev_b32_e32 v122, 16, v61
	v_and_b32_e32 v123, 0xffff0000, v61
	v_lshlrev_b32_e32 v124, 16, v62
	v_and_b32_e32 v125, 0xffff0000, v62
	v_lshlrev_b32_e32 v126, 16, v63
	v_and_b32_e32 v127, 0xffff0000, v63
	v_fmac_f32_e32 v136, v120, v120
	v_fmac_f32_e32 v137, v121, v121
	v_fmac_f32_e32 v138, v122, v122
	v_fmac_f32_e32 v139, v123, v123
	v_fmac_f32_e32 v136, v124, v124
	v_fmac_f32_e32 v137, v125, v125
	v_fmac_f32_e32 v138, v126, v126
	v_fmac_f32_e32 v139, v127, v127
	v_add_f32_e32 v136, v136, v137
	v_add_f32_e32 v138, v138, v139
	v_add_f32_e32 v136, v136, v138
	s_nop 1
	v_add_f32_dpp v136, v136, v136 quad_perm:[1,0,3,2] row_mask:0xf bank_mask:0xf
	s_nop 1
	v_add_f32_dpp v136, v136, v136 quad_perm:[2,3,0,1] row_mask:0xf bank_mask:0xf
	s_nop 1
	v_add_f32_dpp v136, v136, v136 row_half_mirror row_mask:0xf bank_mask:0xf
	s_nop 1
	v_add_f32_dpp v136, v136, v136 row_mirror row_mask:0xf bank_mask:0xf
	s_nop 1
	v_readlane_b32 s28, v136, 0
	v_readlane_b32 s29, v136, 16
	v_readlane_b32 s30, v136, 32
	v_readlane_b32 s31, v136, 48
	s_nop 1
	v_mov_b32_e32 v140, s28
	v_add_f32_e32 v140, s29, v140
	v_add_f32_e32 v140, s30, v140
	v_add_f32_e32 v140, s31, v140
	v_mov_b32_e32 v141, s25
	v_fma_f32 v140, v140, s24, v141
	v_rsq_f32_e32 v142, v140
	v_mul_f32_e32 v140, 0.5, v140
	v_mul_f32_e32 v141, v140, v142
	v_fma_f32 v141, -v141, v142, 0.5
	v_fma_f32 v142, v142, v141, v142
	v_mov_b32_e32 v136, 0
	v_mov_b32_e32 v137, 0
	v_mov_b32_e32 v138, 0
	v_mov_b32_e32 v139, 0
	v_lshlrev_b32_e32 v140, 16, v32
	v_and_b32_e32 v141, 0xffff0000, v32
	v_mul_f32_e32 v96, v96, v142
	v_mul_f32_e32 v97, v97, v142
	v_fma_f32 v96, v96, v0, v140
	v_fma_f32 v97, v97, v1, v141
	v_fmac_f32_e32 v136, v96, v96
	v_fmac_f32_e32 v137, v97, v97
	v_cvt_pk_bf16_f32 v32, v96, v97
	v_lshlrev_b32_e32 v132, 16, v33
	v_and_b32_e32 v133, 0xffff0000, v33
	v_mul_f32_e32 v98, v98, v142
	v_mul_f32_e32 v99, v99, v142
	v_fma_f32 v98, v98, v2, v132
	v_fma_f32 v99, v99, v3, v133
	v_fmac_f32_e32 v138, v98, v98
	v_fmac_f32_e32 v139, v99, v99
	v_cvt_pk_bf16_f32 v33, v98, v99
	v_lshlrev_b32_e32 v140, 16, v34
	v_and_b32_e32 v141, 0xffff0000, v34
	v_mul_f32_e32 v100, v100, v142
	v_mul_f32_e32 v101, v101, v142
	v_fma_f32 v100, v100, v4, v140
	v_fma_f32 v101, v101, v5, v141
	v_fmac_f32_e32 v136, v100, v100
	v_fmac_f32_e32 v137, v101, v101
	v_cvt_pk_bf16_f32 v34, v100, v101
	v_lshlrev_b32_e32 v132, 16, v35
	v_and_b32_e32 v133, 0xffff0000, v35
	v_mul_f32_e32 v102, v102, v142
	v_mul_f32_e32 v103, v103, v142
	v_fma_f32 v102, v102, v6, v132
	v_fma_f32 v103, v103, v7, v133
	v_fmac_f32_e32 v138, v102, v102
	v_fmac_f32_e32 v139, v103, v103
	v_cvt_pk_bf16_f32 v35, v102, v103
	global_store_dwordx4 v134, v[32:35], s[0:1]
	v_lshlrev_b32_e32 v140, 16, v36
	v_and_b32_e32 v141, 0xffff0000, v36
	v_mul_f32_e32 v104, v104, v142
	v_mul_f32_e32 v105, v105, v142
	v_fma_f32 v104, v104, v8, v140
	v_fma_f32 v105, v105, v9, v141
	v_fmac_f32_e32 v136, v104, v104
	v_fmac_f32_e32 v137, v105, v105
	v_cvt_pk_bf16_f32 v36, v104, v105
	v_lshlrev_b32_e32 v132, 16, v37
	v_and_b32_e32 v133, 0xffff0000, v37
	v_mul_f32_e32 v106, v106, v142
	v_mul_f32_e32 v107, v107, v142
	v_fma_f32 v106, v106, v10, v132
	v_fma_f32 v107, v107, v11, v133
	v_fmac_f32_e32 v138, v106, v106
	v_fmac_f32_e32 v139, v107, v107
	v_cvt_pk_bf16_f32 v37, v106, v107
	v_lshlrev_b32_e32 v140, 16, v38
	v_and_b32_e32 v141, 0xffff0000, v38
	v_mul_f32_e32 v108, v108, v142
	v_mul_f32_e32 v109, v109, v142
	v_fma_f32 v108, v108, v12, v140
	v_fma_f32 v109, v109, v13, v141
	v_fmac_f32_e32 v136, v108, v108
	v_fmac_f32_e32 v137, v109, v109
	v_cvt_pk_bf16_f32 v38, v108, v109
	v_lshlrev_b32_e32 v132, 16, v39
	v_and_b32_e32 v133, 0xffff0000, v39
	v_mul_f32_e32 v110, v110, v142
	v_mul_f32_e32 v111, v111, v142
	v_fma_f32 v110, v110, v14, v132
	v_fma_f32 v111, v111, v15, v133
	v_fmac_f32_e32 v138, v110, v110
	v_fmac_f32_e32 v139, v111, v111
; DI unsigned pk2(float lo, float hi) { return pg8::cvt_pk_bf16(lo, hi); }
; DI f32x4 bf4(v2u raw) { return (f32x4){bf2f((unsigned short)(raw.x & 0xffffu)), bf2f((unsigned short)(raw.x >> 16)), bf2f((unsigned short)(raw.y & 0xffffu)), bf2f((unsigned short)(raw.y >> 16))}; }
; template <bool HAS_MIX, bool WRITE_H, int NR, bool SRC16, bool DST16>
; DI void row_pass(const void* xsrc, const bf16* mix, void* xdst, float* rsd, size_t rstride, int rsstride, const float* gpost, int lane) {
;     ...
;     if (HAS_MIX) {
;         float rstd[NR];
; #pragma unroll
;         for (int rr = 0; rr < NR; ++rr) { float ss = 0.f;
; #pragma unroll
;             for (int j = 0; j < 8; ++j) { const f32x4 m = bf4(mr[rr][j]); ss += (m.x * m.x + m.y * m.y) + (m.z * m.z + m.w * m.w); }
;             rstd[rr] = 1.0f / sqrtf(wave_sum(ss) * (1.0f / D) + EPS); }
; #pragma unroll
;         for (int j = 0; j < 8; ++j) { const f32x4 g = ((const f32x4*)gpost)[lane + 64 * j];
; #pragma unroll
;             for (int rr = 0; rr < NR; ++rr) { v[rr][j] = v[rr][j] + bf4(mr[rr][j]) * rstd[rr] * g;
;                 if (DST16) { v2u w; w.x = pk2(v[rr][j].x, v[rr][j].y); w.y = pk2(v[rr][j].z, v[rr][j].w); ((v2u*)((bf16*)xdst + rr * rstride))[lane + 64 * j] = w; }
;                 else __builtin_nontemporal_store(v[rr][j], (f32x4*)((float*)xdst + rr * rstride) + lane + 64 * j); } }
;     }
;     if (WRITE_H) {
; #pragma unroll
;         for (int rr = 0; rr < NR; ++rr) { float ss = 0.f;
; #pragma unroll
;             for (int j = 0; j < 8; ++j) ss += (v[rr][j].x * v[rr][j].x + v[rr][j].y * v[rr][j].y) + (v[rr][j].z * v[rr][j].z + v[rr][j].w * v[rr][j].w);
;             const float rstd = 1.0f / sqrtf(wave_sum(ss) * (1.0f / D) + EPS);
;             if (lane == 0) rsd[rr * rsstride] = rstd; }
	v_cvt_pk_bf16_f32 v39, v110, v111
	global_store_dwordx4 v134, v[36:39], s[0:1] offset:1024
	v_lshlrev_b32_e32 v140, 16, v40
	v_and_b32_e32 v141, 0xffff0000, v40
	v_mul_f32_e32 v112, v112, v142
	v_mul_f32_e32 v113, v113, v142
	v_fma_f32 v112, v112, v16, v140
	v_fma_f32 v113, v113, v17, v141
	v_fmac_f32_e32 v136, v112, v112
	v_fmac_f32_e32 v137, v113, v113
	v_cvt_pk_bf16_f32 v40, v112, v113
	v_lshlrev_b32_e32 v132, 16, v41
	v_and_b32_e32 v133, 0xffff0000, v41
	v_mul_f32_e32 v114, v114, v142
	v_mul_f32_e32 v115, v115, v142
	v_fma_f32 v114, v114, v18, v132
	v_fma_f32 v115, v115, v19, v133
	v_fmac_f32_e32 v138, v114, v114
	v_fmac_f32_e32 v139, v115, v115
	v_cvt_pk_bf16_f32 v41, v114, v115
	v_lshlrev_b32_e32 v140, 16, v42
	v_and_b32_e32 v141, 0xffff0000, v42
	v_mul_f32_e32 v116, v116, v142
	v_mul_f32_e32 v117, v117, v142
	v_fma_f32 v116, v116, v20, v140
	v_fma_f32 v117, v117, v21, v141
	v_fmac_f32_e32 v136, v116, v116
	v_fmac_f32_e32 v137, v117, v117
	v_cvt_pk_bf16_f32 v42, v116, v117
	v_lshlrev_b32_e32 v132, 16, v43
	v_and_b32_e32 v133, 0xffff0000, v43
	v_mul_f32_e32 v118, v118, v142
	v_mul_f32_e32 v119, v119, v142
	v_fma_f32 v118, v118, v22, v132
	v_fma_f32 v119, v119, v23, v133
	v_fmac_f32_e32 v138, v118, v118
	v_fmac_f32_e32 v139, v119, v119
	v_cvt_pk_bf16_f32 v43, v118, v119
	global_store_dwordx4 v134, v[40:43], s[0:1] offset:2048
	v_lshlrev_b32_e32 v140, 16, v44
	v_and_b32_e32 v141, 0xffff0000, v44
	v_mul_f32_e32 v120, v120, v142
	v_mul_f32_e32 v121, v121, v142
	v_fma_f32 v120, v120, v24, v140
	v_fma_f32 v121, v121, v25, v141
	v_fmac_f32_e32 v136, v120, v120
	v_fmac_f32_e32 v137, v121, v121
	v_cvt_pk_bf16_f32 v44, v120, v121
	v_lshlrev_b32_e32 v132, 16, v45
	v_and_b32_e32 v133, 0xffff0000, v45
	v_mul_f32_e32 v122, v122, v142
	v_mul_f32_e32 v123, v123, v142
	v_fma_f32 v122, v122, v26, v132
	v_fma_f32 v123, v123, v27, v133
	v_fmac_f32_e32 v138, v122, v122
	v_fmac_f32_e32 v139, v123, v123
	v_cvt_pk_bf16_f32 v45, v122, v123
	v_lshlrev_b32_e32 v140, 16, v46
	v_and_b32_e32 v141, 0xffff0000, v46
	v_mul_f32_e32 v124, v124, v142
	v_mul_f32_e32 v125, v125, v142
	v_fma_f32 v124, v124, v28, v140
	v_fma_f32 v125, v125, v29, v141
	v_fmac_f32_e32 v136, v124, v124
	v_fmac_f32_e32 v137, v125, v125
	v_cvt_pk_bf16_f32 v46, v124, v125
	v_lshlrev_b32_e32 v132, 16, v47
	v_and_b32_e32 v133, 0xffff0000, v47
	v_mul_f32_e32 v126, v126, v142
	v_mul_f32_e32 v127, v127, v142
	v_fma_f32 v126, v126, v30, v132
	v_fma_f32 v127, v127, v31, v133
	v_fmac_f32_e32 v138, v126, v126
	v_fmac_f32_e32 v139, v127, v127
	v_cvt_pk_bf16_f32 v47, v126, v127
	global_store_dwordx4 v134, v[44:47], s[0:1] offset:3072
	v_add_f32_e32 v136, v136, v137
	v_add_f32_e32 v138, v138, v139
	v_add_f32_e32 v136, v136, v138
	s_nop 1
	v_add_f32_dpp v136, v136, v136 quad_perm:[1,0,3,2] row_mask:0xf bank_mask:0xf
	s_nop 1
	v_add_f32_dpp v136, v136, v136 quad_perm:[2,3,0,1] row_mask:0xf bank_mask:0xf
	s_nop 1
	v_add_f32_dpp v136, v136, v136 row_half_mirror row_mask:0xf bank_mask:0xf
	s_nop 1
	v_add_f32_dpp v136, v136, v136 row_mirror row_mask:0xf bank_mask:0xf
	s_nop 1
	v_readlane_b32 s28, v136, 0
	v_readlane_b32 s29, v136, 16
	v_readlane_b32 s30, v136, 32
	v_readlane_b32 s31, v136, 48
	s_nop 1
	v_mov_b32_e32 v140, s28
	v_add_f32_e32 v140, s29, v140
	v_add_f32_e32 v140, s30, v140
	v_add_f32_e32 v140, s31, v140
	v_mov_b32_e32 v141, s25
	v_fma_f32 v140, v140, s24, v141
	v_rsq_f32_e32 v128, v140
	v_mul_f32_e32 v140, 0.5, v140
	v_mul_f32_e32 v141, v140, v128
	v_fma_f32 v141, -v141, v128, 0.5
	v_fma_f32 v128, v128, v141, v128
	s_lshl_b32 s26, s20, 2
	s_add_u32 s26, s4, s26
	s_addc_u32 s27, s5, 0
	v_mov_b32_e32 v140, 0
	s_mov_b64 exec, 1
	global_store_dword v140, v128, s[26:27]
	s_mov_b64 exec, -1
	s_waitcnt vmcnt(5)
	v_mov_b32_e32 v136, 0
	v_mov_b32_e32 v137, 0
	v_mov_b32_e32 v138, 0
	v_mov_b32_e32 v139, 0
	v_lshlrev_b32_e32 v96, 16, v80
	v_and_b32_e32 v97, 0xffff0000, v80
	v_lshlrev_b32_e32 v98, 16, v81
	v_and_b32_e32 v99, 0xffff0000, v81
	v_lshlrev_b32_e32 v100, 16, v82
	v_and_b32_e32 v101, 0xffff0000, v82
	v_lshlrev_b32_e32 v102, 16, v83
	v_and_b32_e32 v103, 0xffff0000, v83
	v_fmac_f32_e32 v136, v96, v96
	v_fmac_f32_e32 v137, v97, v97
	v_fmac_f32_e32 v138, v98, v98
	v_fmac_f32_e32 v139, v99, v99
	v_fmac_f32_e32 v136, v100, v100
	v_fmac_f32_e32 v137, v101, v101
	v_fmac_f32_e32 v138, v102, v102
	v_fmac_f32_e32 v139, v103, v103
	v_lshlrev_b32_e32 v104, 16, v84
	v_and_b32_e32 v105, 0xffff0000, v84
	v_lshlrev_b32_e32 v106, 16, v85
	v_and_b32_e32 v107, 0xffff0000, v85
	v_lshlrev_b32_e32 v108, 16, v86
	v_and_b32_e32 v109, 0xffff0000, v86
	v_lshlrev_b32_e32 v110, 16, v87
	v_and_b32_e32 v111, 0xffff0000, v87
	v_fmac_f32_e32 v136, v104, v104
	v_fmac_f32_e32 v137, v105, v105
	v_fmac_f32_e32 v138, v106, v106
	v_fmac_f32_e32 v139, v107, v107
	v_fmac_f32_e32 v136, v108, v108
	v_fmac_f32_e32 v137, v109, v109
	v_fmac_f32_e32 v138, v110, v110
	v_fmac_f32_e32 v139, v111, v111
	v_lshlrev_b32_e32 v112, 16, v88
	v_and_b32_e32 v113, 0xffff0000, v88
	v_lshlrev_b32_e32 v114, 16, v89
	v_and_b32_e32 v115, 0xffff0000, v89
	v_lshlrev_b32_e32 v116, 16, v90
	v_and_b32_e32 v117, 0xffff0000, v90
	v_lshlrev_b32_e32 v118, 16, v91
	v_and_b32_e32 v119, 0xffff0000, v91
	v_fmac_f32_e32 v136, v112, v112
	v_fmac_f32_e32 v137, v113, v113
	v_fmac_f32_e32 v138, v114, v114
	v_fmac_f32_e32 v139, v115, v115
	v_fmac_f32_e32 v136, v116, v116
	v_fmac_f32_e32 v137, v117, v117
	v_fmac_f32_e32 v138, v118, v118
	v_fmac_f32_e32 v139, v119, v119
	v_lshlrev_b32_e32 v120, 16, v92
	v_and_b32_e32 v121, 0xffff0000, v92
	v_lshlrev_b32_e32 v122, 16, v93
	v_and_b32_e32 v123, 0xffff0000, v93
	v_lshlrev_b32_e32 v124, 16, v94
	v_and_b32_e32 v125, 0xffff0000, v94
; DI unsigned pk2(float lo, float hi) { return pg8::cvt_pk_bf16(lo, hi); }
; DI f32x4 bf4(v2u raw) { return (f32x4){bf2f((unsigned short)(raw.x & 0xffffu)), bf2f((unsigned short)(raw.x >> 16)), bf2f((unsigned short)(raw.y & 0xffffu)), bf2f((unsigned short)(raw.y >> 16))}; }
; template <bool HAS_MIX, bool WRITE_H, int NR, bool SRC16, bool DST16>
; DI void row_pass(const void* xsrc, const bf16* mix, void* xdst, float* rsd, size_t rstride, int rsstride, const float* gpost, int lane) {
;     ...
;     if (HAS_MIX) {
;         float rstd[NR];
; #pragma unroll
;         for (int rr = 0; rr < NR; ++rr) { float ss = 0.f;
; #pragma unroll
;             for (int j = 0; j < 8; ++j) { const f32x4 m = bf4(mr[rr][j]); ss += (m.x * m.x + m.y * m.y) + (m.z * m.z + m.w * m.w); }
;             rstd[rr] = 1.0f / sqrtf(wave_sum(ss) * (1.0f / D) + EPS); }
; #pragma unroll
;         for (int j = 0; j < 8; ++j) { const f32x4 g = ((const f32x4*)gpost)[lane + 64 * j];
; #pragma unroll
;             for (int rr = 0; rr < NR; ++rr) { v[rr][j] = v[rr][j] + bf4(mr[rr][j]) * rstd[rr] * g;
;                 if (DST16) { v2u w; w.x = pk2(v[rr][j].x, v[rr][j].y); w.y = pk2(v[rr][j].z, v[rr][j].w); ((v2u*)((bf16*)xdst + rr * rstride))[lane + 64 * j] = w; }
;                 else __builtin_nontemporal_store(v[rr][j], (f32x4*)((float*)xdst + rr * rstride) + lane + 64 * j); } }
	v_lshlrev_b32_e32 v126, 16, v95
	v_and_b32_e32 v127, 0xffff0000, v95
	v_fmac_f32_e32 v136, v120, v120
	v_fmac_f32_e32 v137, v121, v121
	v_fmac_f32_e32 v138, v122, v122
	v_fmac_f32_e32 v139, v123, v123
	v_fmac_f32_e32 v136, v124, v124
	v_fmac_f32_e32 v137, v125, v125
	v_fmac_f32_e32 v138, v126, v126
	v_fmac_f32_e32 v139, v127, v127
	v_add_f32_e32 v136, v136, v137
	v_add_f32_e32 v138, v138, v139
	v_add_f32_e32 v136, v136, v138
	s_nop 1
	v_add_f32_dpp v136, v136, v136 quad_perm:[1,0,3,2] row_mask:0xf bank_mask:0xf
	s_nop 1
	v_add_f32_dpp v136, v136, v136 quad_perm:[2,3,0,1] row_mask:0xf bank_mask:0xf
	s_nop 1
	v_add_f32_dpp v136, v136, v136 row_half_mirror row_mask:0xf bank_mask:0xf
	s_nop 1
	v_add_f32_dpp v136, v136, v136 row_mirror row_mask:0xf bank_mask:0xf
	s_nop 1
	v_readlane_b32 s28, v136, 0
	v_readlane_b32 s29, v136, 16
	v_readlane_b32 s30, v136, 32
	v_readlane_b32 s31, v136, 48
	s_nop 1
	v_mov_b32_e32 v140, s28
	v_add_f32_e32 v140, s29, v140
	v_add_f32_e32 v140, s30, v140
	v_add_f32_e32 v140, s31, v140
	v_mov_b32_e32 v141, s25
	v_fma_f32 v140, v140, s24, v141
	v_rsq_f32_e32 v142, v140
	v_mul_f32_e32 v140, 0.5, v140
	v_mul_f32_e32 v141, v140, v142
	v_fma_f32 v141, -v141, v142, 0.5
	v_fma_f32 v142, v142, v141, v142
	v_mov_b32_e32 v136, 0
	v_mov_b32_e32 v137, 0
	v_mov_b32_e32 v138, 0
	v_mov_b32_e32 v139, 0
	v_lshlrev_b32_e32 v140, 16, v64
	v_and_b32_e32 v141, 0xffff0000, v64
	v_mul_f32_e32 v96, v96, v142
	v_mul_f32_e32 v97, v97, v142
	v_fma_f32 v96, v96, v0, v140
	v_fma_f32 v97, v97, v1, v141
	v_fmac_f32_e32 v136, v96, v96
	v_fmac_f32_e32 v137, v97, v97
	v_cvt_pk_bf16_f32 v64, v96, v97
	v_lshlrev_b32_e32 v132, 16, v65
	v_and_b32_e32 v133, 0xffff0000, v65
	v_mul_f32_e32 v98, v98, v142
	v_mul_f32_e32 v99, v99, v142
	v_fma_f32 v98, v98, v2, v132
	v_fma_f32 v99, v99, v3, v133
	v_fmac_f32_e32 v138, v98, v98
	v_fmac_f32_e32 v139, v99, v99
	v_cvt_pk_bf16_f32 v65, v98, v99
	v_lshlrev_b32_e32 v140, 16, v66
	v_and_b32_e32 v141, 0xffff0000, v66
	v_mul_f32_e32 v100, v100, v142
	v_mul_f32_e32 v101, v101, v142
	v_fma_f32 v100, v100, v4, v140
	v_fma_f32 v101, v101, v5, v141
	v_fmac_f32_e32 v136, v100, v100
	v_fmac_f32_e32 v137, v101, v101
	v_cvt_pk_bf16_f32 v66, v100, v101
	v_lshlrev_b32_e32 v132, 16, v67
	v_and_b32_e32 v133, 0xffff0000, v67
	v_mul_f32_e32 v102, v102, v142
	v_mul_f32_e32 v103, v103, v142
	v_fma_f32 v102, v102, v6, v132
	v_fma_f32 v103, v103, v7, v133
	v_fmac_f32_e32 v138, v102, v102
	v_fmac_f32_e32 v139, v103, v103
	v_cvt_pk_bf16_f32 v67, v102, v103
	global_store_dwordx4 v135, v[64:67], s[0:1]
	v_lshlrev_b32_e32 v140, 16, v68
	v_and_b32_e32 v141, 0xffff0000, v68
	v_mul_f32_e32 v104, v104, v142
	v_mul_f32_e32 v105, v105, v142
	v_fma_f32 v104, v104, v8, v140
	v_fma_f32 v105, v105, v9, v141
	v_fmac_f32_e32 v136, v104, v104
	v_fmac_f32_e32 v137, v105, v105
	v_cvt_pk_bf16_f32 v68, v104, v105
	v_lshlrev_b32_e32 v132, 16, v69
	v_and_b32_e32 v133, 0xffff0000, v69
	v_mul_f32_e32 v106, v106, v142
	v_mul_f32_e32 v107, v107, v142
	v_fma_f32 v106, v106, v10, v132
	v_fma_f32 v107, v107, v11, v133
	v_fmac_f32_e32 v138, v106, v106
	v_fmac_f32_e32 v139, v107, v107
	v_cvt_pk_bf16_f32 v69, v106, v107
	v_lshlrev_b32_e32 v140, 16, v70
	v_and_b32_e32 v141, 0xffff0000, v70
	v_mul_f32_e32 v108, v108, v142
	v_mul_f32_e32 v109, v109, v142
	v_fma_f32 v108, v108, v12, v140
	v_fma_f32 v109, v109, v13, v141
	v_fmac_f32_e32 v136, v108, v108
	v_fmac_f32_e32 v137, v109, v109
	v_cvt_pk_bf16_f32 v70, v108, v109
	v_lshlrev_b32_e32 v132, 16, v71
	v_and_b32_e32 v133, 0xffff0000, v71
	v_mul_f32_e32 v110, v110, v142
	v_mul_f32_e32 v111, v111, v142
	v_fma_f32 v110, v110, v14, v132
	v_fma_f32 v111, v111, v15, v133
	v_fmac_f32_e32 v138, v110, v110
	v_fmac_f32_e32 v139, v111, v111
; DI unsigned pk2(float lo, float hi) { return pg8::cvt_pk_bf16(lo, hi); }
; DI f32x4 bf4(v2u raw) { return (f32x4){bf2f((unsigned short)(raw.x & 0xffffu)), bf2f((unsigned short)(raw.x >> 16)), bf2f((unsigned short)(raw.y & 0xffffu)), bf2f((unsigned short)(raw.y >> 16))}; }
; template <bool HAS_MIX, bool WRITE_H, int NR, bool SRC16, bool DST16>
; DI void row_pass(const void* xsrc, const bf16* mix, void* xdst, float* rsd, size_t rstride, int rsstride, const float* gpost, int lane) {
;     ...
; #pragma unroll
;         for (int j = 0; j < 8; ++j) { const f32x4 g = ((const f32x4*)gpost)[lane + 64 * j];
; #pragma unroll
;             for (int rr = 0; rr < NR; ++rr) { v[rr][j] = v[rr][j] + bf4(mr[rr][j]) * rstd[rr] * g;
;                 if (DST16) { v2u w; w.x = pk2(v[rr][j].x, v[rr][j].y); w.y = pk2(v[rr][j].z, v[rr][j].w); ((v2u*)((bf16*)xdst + rr * rstride))[lane + 64 * j] = w; }
;                 else __builtin_nontemporal_store(v[rr][j], (f32x4*)((float*)xdst + rr * rstride) + lane + 64 * j); } }
;     }
;     if (WRITE_H) {
; #pragma unroll
;         for (int rr = 0; rr < NR; ++rr) { float ss = 0.f;
; #pragma unroll
;             for (int j = 0; j < 8; ++j) ss += (v[rr][j].x * v[rr][j].x + v[rr][j].y * v[rr][j].y) + (v[rr][j].z * v[rr][j].z + v[rr][j].w * v[rr][j].w);
;             const float rstd = 1.0f / sqrtf(wave_sum(ss) * (1.0f / D) + EPS);
;             if (lane == 0) rsd[rr * rsstride] = rstd; }
	v_cvt_pk_bf16_f32 v71, v110, v111
	global_store_dwordx4 v135, v[68:71], s[0:1] offset:1024
	v_lshlrev_b32_e32 v140, 16, v72
	v_and_b32_e32 v141, 0xffff0000, v72
	v_mul_f32_e32 v112, v112, v142
	v_mul_f32_e32 v113, v113, v142
	v_fma_f32 v112, v112, v16, v140
	v_fma_f32 v113, v113, v17, v141
	v_fmac_f32_e32 v136, v112, v112
	v_fmac_f32_e32 v137, v113, v113
	v_cvt_pk_bf16_f32 v72, v112, v113
	v_lshlrev_b32_e32 v132, 16, v73
	v_and_b32_e32 v133, 0xffff0000, v73
	v_mul_f32_e32 v114, v114, v142
	v_mul_f32_e32 v115, v115, v142
	v_fma_f32 v114, v114, v18, v132
	v_fma_f32 v115, v115, v19, v133
	v_fmac_f32_e32 v138, v114, v114
	v_fmac_f32_e32 v139, v115, v115
	v_cvt_pk_bf16_f32 v73, v114, v115
	v_lshlrev_b32_e32 v140, 16, v74
	v_and_b32_e32 v141, 0xffff0000, v74
	v_mul_f32_e32 v116, v116, v142
	v_mul_f32_e32 v117, v117, v142
	v_fma_f32 v116, v116, v20, v140
	v_fma_f32 v117, v117, v21, v141
	v_fmac_f32_e32 v136, v116, v116
	v_fmac_f32_e32 v137, v117, v117
	v_cvt_pk_bf16_f32 v74, v116, v117
	v_lshlrev_b32_e32 v132, 16, v75
	v_and_b32_e32 v133, 0xffff0000, v75
	v_mul_f32_e32 v118, v118, v142
	v_mul_f32_e32 v119, v119, v142
	v_fma_f32 v118, v118, v22, v132
	v_fma_f32 v119, v119, v23, v133
	v_fmac_f32_e32 v138, v118, v118
	v_fmac_f32_e32 v139, v119, v119
	v_cvt_pk_bf16_f32 v75, v118, v119
	global_store_dwordx4 v135, v[72:75], s[0:1] offset:2048
	v_lshlrev_b32_e32 v140, 16, v76
	v_and_b32_e32 v141, 0xffff0000, v76
	v_mul_f32_e32 v120, v120, v142
	v_mul_f32_e32 v121, v121, v142
	v_fma_f32 v120, v120, v24, v140
	v_fma_f32 v121, v121, v25, v141
	v_fmac_f32_e32 v136, v120, v120
	v_fmac_f32_e32 v137, v121, v121
	v_cvt_pk_bf16_f32 v76, v120, v121
	v_lshlrev_b32_e32 v132, 16, v77
	v_and_b32_e32 v133, 0xffff0000, v77
	v_mul_f32_e32 v122, v122, v142
	v_mul_f32_e32 v123, v123, v142
	v_fma_f32 v122, v122, v26, v132
	v_fma_f32 v123, v123, v27, v133
	v_fmac_f32_e32 v138, v122, v122
	v_fmac_f32_e32 v139, v123, v123
	v_cvt_pk_bf16_f32 v77, v122, v123
	v_lshlrev_b32_e32 v140, 16, v78
	v_and_b32_e32 v141, 0xffff0000, v78
	v_mul_f32_e32 v124, v124, v142
	v_mul_f32_e32 v125, v125, v142
	v_fma_f32 v124, v124, v28, v140
	v_fma_f32 v125, v125, v29, v141
	v_fmac_f32_e32 v136, v124, v124
	v_fmac_f32_e32 v137, v125, v125
	v_cvt_pk_bf16_f32 v78, v124, v125
	v_lshlrev_b32_e32 v132, 16, v79
	v_and_b32_e32 v133, 0xffff0000, v79
	v_mul_f32_e32 v126, v126, v142
	v_mul_f32_e32 v127, v127, v142
	v_fma_f32 v126, v126, v30, v132
	v_fma_f32 v127, v127, v31, v133
	v_fmac_f32_e32 v138, v126, v126
	v_fmac_f32_e32 v139, v127, v127
	v_cvt_pk_bf16_f32 v79, v126, v127
	global_store_dwordx4 v135, v[76:79], s[0:1] offset:3072
	v_add_f32_e32 v136, v136, v137
	v_add_f32_e32 v138, v138, v139
	v_add_f32_e32 v136, v136, v138
	s_nop 1
	v_add_f32_dpp v136, v136, v136 quad_perm:[1,0,3,2] row_mask:0xf bank_mask:0xf
	s_nop 1
	v_add_f32_dpp v136, v136, v136 quad_perm:[2,3,0,1] row_mask:0xf bank_mask:0xf
	s_nop 1
	v_add_f32_dpp v136, v136, v136 row_half_mirror row_mask:0xf bank_mask:0xf
	s_nop 1
	v_add_f32_dpp v136, v136, v136 row_mirror row_mask:0xf bank_mask:0xf
	s_nop 1
	v_readlane_b32 s28, v136, 0
	v_readlane_b32 s29, v136, 16
	v_readlane_b32 s30, v136, 32
	v_readlane_b32 s31, v136, 48
	s_nop 1
	v_mov_b32_e32 v140, s28
	v_add_f32_e32 v140, s29, v140
	v_add_f32_e32 v140, s30, v140
	v_add_f32_e32 v140, s31, v140
	v_mov_b32_e32 v141, s25
	v_fma_f32 v140, v140, s24, v141
	v_rsq_f32_e32 v128, v140
	v_mul_f32_e32 v140, 0.5, v140
	v_mul_f32_e32 v141, v140, v128
	v_fma_f32 v141, -v141, v128, 0.5
	v_fma_f32 v128, v128, v141, v128
	s_lshl_b32 s26, s22, 2
	s_add_u32 s26, s4, s26
	s_addc_u32 s27, s5, 0
	v_mov_b32_e32 v140, 0
	s_mov_b64 exec, 1
	global_store_dword v140, v128, s[26:27]
	s_mov_b64 exec, -1

; #define PG8_STAGE(bufoff, gbase, voff) do { _Pragma("unroll") for (int _i = 0; _i < 2; ++_i) \
;         __builtin_amdgcn_global_load_lds((const unsigned*)((const char*)(gbase) + (voff)[_i]), (PG8_LAS unsigned*)(lds + (bufoff) + ldsw + _i * 8192), 16, 0, 0); } while (0)
; #define PG8_WAIT_V(n) asm volatile("s_waitcnt vmcnt(" #n ")" ::: "memory")
; #define PG8_BAR __builtin_amdgcn_s_barrier()
; template <class Epi, class Sched, bool ALIGN_EPI = false, bool SP2 = false>
; __device__ __forceinline__ void gemm_phase(PG8_LAS unsigned char* lds, const Gemm g, const Sched& S, const Epi& E) {
;     ...
;     for (int i = 0; i < 2; ++i) { int R, C; stage_rc(tid * 16 + i * 8192, R, C); const int Rb = Epi::PERM ? ((R & ~31) + perm32(R & 31)) : R;
;         voffA[i] = (unsigned)(R * K + C) * 2u; voffB[i] = (unsigned)(Rb * K + C) * 2u; }
;     const size_t kstep = (size_t)(BK * 2);
;     const size_t hstep = (size_t)HALF * K * 2;
;     const size_t tstep = 2 * hstep;
;     const unsigned ldsw = (unsigned)wid * 1024u;
;     const int aoff = lds_byte(wr * 64 + fr, fq * 8), boff = lds_byte(wc * 32 + fr, fq * 8);
;     ...
;         PG8_STAGE(PG8_SB(0, 0), cB, voffB); PG8_STAGE(PG8_SB(0, 1), cB + hstep, voffB); PG8_STAGE(PG8_SA(0, 0), cA, voffA); PG8_STAGE(PG8_SA(0, 1), cA + hstep, voffA);
;         if (wr == 1) PG8_BAR;
;         PG8_WAIT_V(2); PG8_BAR;
;         PG8_STAGE(PG8_SB(1, 0), cB + kstep, voffB); PG8_STAGE(PG8_SA(1, 0), cA + kstep, voffA); PG8_STAGE(PG8_SB(1, 1), cB + hstep + kstep, voffB);
;         PG8_WAIT_V(6); PG8_BAR;
.LBB0_290:
	s_add_i32 m0, s68, 0x18000
	v_lshl_add_u64 v[8:9], v[8:9], 0, s[72:73]
	s_waitcnt vmcnt(2)
	s_barrier
	global_load_lds_dwordx4 v[8:9], off
	v_lshl_add_u64 v[4:5], v[4:5], 0, s[72:73]
	s_add_i32 m0, s68, 0x1a000
	s_add_i32 s88, s68, 0x8000
	global_load_lds_dwordx4 v[4:5], off
	v_lshl_add_u64 v[4:5], v[6:7], 0, s[72:73]
	s_mov_b32 m0, s88
	s_add_i32 s95, s68, 0xa000
	global_load_lds_dwordx4 v[4:5], off
	v_lshl_add_u64 v[4:5], v[10:11], 0, s[72:73]
	s_mov_b32 m0, s95
	v_lshl_add_u64 v[2:3], v[2:3], 0, s[72:73]
	global_load_lds_dwordx4 v[4:5], off
	s_add_i32 m0, s68, 0x1c000
	v_lshl_add_u64 v[0:1], v[0:1], 0, s[72:73]
	global_load_lds_dwordx4 v[2:3], off
	s_add_i32 m0, s68, 0x1e000
	s_xor_b64 s[58:59], s[4:5], -1
	global_load_lds_dwordx4 v[0:1], off
	v_lshrrev_b32_e32 v1, 1, v12
	v_and_b32_e32 v1, 24, v1
	v_and_b32_e32 v0, 15, v12
	v_lshlrev_b32_e32 v2, 1, v1
	v_lshl_or_b32 v131, s7, 6, v0
	v_lshl_or_b32 v0, v0, 6, v2
	v_lshlrev_b32_e32 v2, 2, v12
	s_lshl_b32 s4, s7, 13
	v_and_b32_e32 v2, 32, v2
	v_bitop3_b32 v3, v0, s4, v2 bitop3:0xde
	s_lshl_b32 s4, s6, 5
	s_lshr_b32 s97, s33, 6
	s_and_b32 s4, s4, 0x60
	s_lshl_b32 s5, s4, 7
	s_add_i32 s96, s97, -2
	s_cmpk_lt_u32 s43, 0x100
	s_cselect_b64 s[74:75], -1, 0
	s_lshr_b32 s99, s60, 6
	v_bitop3_b32 v171, v0, s5, v2 bitop3:0xde
	v_cvt_f32_u32_e32 v0, s99
	s_ashr_i32 s43, s84, 31
	s_ashr_i32 s89, s2, 31
	s_lshr_b32 s86, s52, 3
	v_rcp_iflag_f32_e32 v0, v0
	s_cmp_lg_u64 s[36:37], 0
	s_cselect_b64 s[76:77], -1, 0
	v_or_b32_e32 v172, s4, v1
	v_mul_f32_e32 v0, 0x4f7ffffe, v0
	v_cvt_u32_f32_e32 v0, v0
	s_sub_i32 s4, 0, s99
	v_mov_b32_e32 v1, v129
	s_waitcnt vmcnt(6)
	v_readfirstlane_b32 s5, v0
	v_add_u32_e32 v0, v18, v16
	v_add_lshl_u32 v0, v0, v17, 1
	s_mul_i32 s4, s4, s5
	v_lshl_add_u64 v[138:139], s[62:63], 0, v[0:1]
	v_add_u32_e32 v0, v15, v13
	s_mul_hi_u32 s4, s5, s4
	v_add_lshl_u32 v0, v0, v14, 1
	s_mov_b32 s53, s63
	s_mov_b32 s93, 0
	s_add_i32 s85, s5, s4
	v_lshl_add_u64 v[140:141], s[62:63], 0, v[0:1]
	v_add_u32_e32 v230, s62, v128
	v_add_u32_e32 v231, s62, v136
	v_add_u32_e32 v232, 0x10000, v171
	v_add_u32_e32 v173, 0, v3
	s_barrier
	s_branch .LBB0_293

; #define PG8_STAGE(bufoff, gbase, voff) do { _Pragma("unroll") for (int _i = 0; _i < 2; ++_i) \
;         __builtin_amdgcn_global_load_lds((const unsigned*)((const char*)(gbase) + (voff)[_i]), (PG8_LAS unsigned*)(lds + (bufoff) + ldsw + _i * 8192), 16, 0, 0); } while (0)
; #define PG8_LDA(dst, b, h) do { _Pragma("unroll") for (int m = 0; m < 4; ++m) _Pragma("unroll") for (int k = 0; k < 2; ++k) dst[m][k] = *(const PG8_LAS bf16x8*)(lds + PG8_SA(b, h) + aoff + m * 2048 + k * 1024); } while (0)
; #define PG8_LDB(dst, b, h) do { _Pragma("unroll") for (int n = 0; n < 2; ++n) _Pragma("unroll") for (int k = 0; k < 2; ++k) dst[n][k] = *(const PG8_LAS bf16x8*)(lds + PG8_SB(b, h) + boff + n * 2048 + k * 1024); } while (0)
; #define PG8_MMA(ai, bj, At, Bt) do { __builtin_amdgcn_s_setprio(1); _Pragma("unroll") for (int m = 0; m < 4; ++m) _Pragma("unroll") for (int n = 0; n < 2; ++n) _Pragma("unroll") for (int k = 0; k < 2; ++k) \
;         acc[ai][bj][m][n] = __builtin_amdgcn_mfma_f32_16x16x32_bf16(Bt[n][k], At[m][k], acc[ai][bj][m][n], 0, 0, 0); __builtin_amdgcn_s_setprio(0); } while (0)
; #define PG8_WAIT_V(n) asm volatile("s_waitcnt vmcnt(" #n ")" ::: "memory")
; #define PG8_WAIT_L(n) asm volatile("s_waitcnt lgkmcnt(" #n ")" ::: "memory")
; #define PG8_BAR __builtin_amdgcn_s_barrier()
; #define PG8_SCHED __builtin_amdgcn_sched_barrier(0)
; template <class Epi, class Sched, bool ALIGN_EPI = false, bool SP2 = false>
; __device__ __forceinline__ void gemm_phase(PG8_LAS unsigned char* lds, const Gemm g, const Sched& S, const Epi& E) {
;     ...
;             PG8_LDB(B0, 0, 0); PG8_LDB(B1, 0, 1); PG8_SCHED; PG8_LDA(At, 0, 0); PG8_STAGE(PG8_SA(1, 1), a1 + hstep, voffA);
;             PG8_WAIT_V(8); PG8_WAIT_L(0); PG8_BAR; PG8_MMA(0, 0, At, B0); PG8_MMA(0, 1, At, B1); PG8_BAR; PG8_SCHED;
;             PG8_LDA(At, 0, 1); PG8_STAGE(PG8_SB(0, 0), b2, voffB); PG8_STAGE(PG8_SB(0, 1), b2 + hstep, voffB); PG8_STAGE(PG8_SA(0, 0), a2, voffA);
;             PG8_WAIT_V(8); PG8_WAIT_L(0); PG8_BAR; PG8_MMA(1, 0, At, B0); PG8_MMA(1, 1, At, B1); PG8_BAR; PG8_SCHED;
.LBB0_300:
	s_add_i32 s82, s8, 2
	s_add_u32 s46, s6, 0x80
	s_addc_u32 s9, s7, 0
	s_cmp_eq_u32 s96, s8
	s_cselect_b32 s9, s79, s9
	s_cselect_b32 s8, s78, s46
	s_cselect_b32 s47, s81, vcc_hi
	s_cselect_b32 s46, s80, vcc_lo
	ds_read_b128 v[142:145], v232
	ds_read_b128 v[146:149], v232 offset:1024
	ds_read_b128 v[174:177], v232 offset:2048
	ds_read_b128 v[178:181], v232 offset:3072
	ds_read_b128 v[182:185], v232 offset:16384
	ds_read_b128 v[186:189], v232 offset:17408
	ds_read_b128 v[190:193], v232 offset:18432
	ds_read_b128 v[194:197], v232 offset:19456
	s_add_i32 m0, s68, 0xc000
	ds_read_b128 v[198:201], v173
	ds_read_b128 v[202:205], v173 offset:1024
	ds_read_b128 v[206:209], v173 offset:2048
	ds_read_b128 v[210:213], v173 offset:3072
	ds_read_b128 v[214:217], v173 offset:4096
	ds_read_b128 v[218:221], v173 offset:5120
	ds_read_b128 v[222:225], v173 offset:6144
	ds_read_b128 v[226:229], v173 offset:7168
	global_load_lds_dwordx4 v140, s[6:7]
	s_add_i32 m0, s68, 0xe000
	s_nop 0
	global_load_lds_dwordx4 v138, s[6:7]
	s_waitcnt vmcnt(8)
	s_waitcnt lgkmcnt(0)
	s_barrier
	s_setprio 1
	v_mfma_f32_16x16x32_bf16 v[124:127], v[142:145], v[198:201], v[124:127]
	v_mfma_f32_16x16x32_bf16 v[120:123], v[174:177], v[198:201], v[120:123]
	v_mfma_f32_16x16x32_bf16 v[108:111], v[142:145], v[206:209], v[108:111]
	v_mfma_f32_16x16x32_bf16 v[104:107], v[174:177], v[206:209], v[104:107]
	v_mfma_f32_16x16x32_bf16 v[92:95], v[142:145], v[214:217], v[92:95]
	v_mfma_f32_16x16x32_bf16 v[88:91], v[174:177], v[214:217], v[88:91]
	v_mfma_f32_16x16x32_bf16 v[76:79], v[142:145], v[222:225], v[76:79]
	v_mfma_f32_16x16x32_bf16 v[72:75], v[174:177], v[222:225], v[72:75]
	v_mfma_f32_16x16x32_bf16 v[124:127], v[146:149], v[202:205], v[124:127]
	v_mfma_f32_16x16x32_bf16 v[120:123], v[178:181], v[202:205], v[120:123]
	v_mfma_f32_16x16x32_bf16 v[108:111], v[146:149], v[210:213], v[108:111]
	v_mfma_f32_16x16x32_bf16 v[104:107], v[178:181], v[210:213], v[104:107]
	v_mfma_f32_16x16x32_bf16 v[92:95], v[146:149], v[218:221], v[92:95]
	v_mfma_f32_16x16x32_bf16 v[88:91], v[178:181], v[218:221], v[88:91]
	v_mfma_f32_16x16x32_bf16 v[76:79], v[146:149], v[226:229], v[76:79]
	v_mfma_f32_16x16x32_bf16 v[72:75], v[178:181], v[226:229], v[72:75]
	s_setprio 0
	s_setprio 1
	v_mfma_f32_16x16x32_bf16 v[116:119], v[182:185], v[198:201], v[116:119]
	v_mfma_f32_16x16x32_bf16 v[112:115], v[190:193], v[198:201], v[112:115]
	v_mfma_f32_16x16x32_bf16 v[100:103], v[182:185], v[206:209], v[100:103]
	v_mfma_f32_16x16x32_bf16 v[96:99], v[190:193], v[206:209], v[96:99]
	v_mfma_f32_16x16x32_bf16 v[84:87], v[182:185], v[214:217], v[84:87]
	v_mfma_f32_16x16x32_bf16 v[80:83], v[190:193], v[214:217], v[80:83]
	v_mfma_f32_16x16x32_bf16 v[68:71], v[182:185], v[222:225], v[68:71]
	v_mfma_f32_16x16x32_bf16 v[64:67], v[190:193], v[222:225], v[64:67]
	v_mfma_f32_16x16x32_bf16 v[116:119], v[186:189], v[202:205], v[116:119]
	v_mfma_f32_16x16x32_bf16 v[112:115], v[194:197], v[202:205], v[112:115]
	v_mfma_f32_16x16x32_bf16 v[100:103], v[186:189], v[210:213], v[100:103]
	v_mfma_f32_16x16x32_bf16 v[96:99], v[194:197], v[210:213], v[96:99]
	v_mfma_f32_16x16x32_bf16 v[84:87], v[186:189], v[218:221], v[84:87]
	v_mfma_f32_16x16x32_bf16 v[80:83], v[194:197], v[218:221], v[80:83]
	v_mfma_f32_16x16x32_bf16 v[68:71], v[186:189], v[226:229], v[68:71]
	v_mfma_f32_16x16x32_bf16 v[64:67], v[194:197], v[226:229], v[64:67]
	s_setprio 0
	s_barrier
	s_add_i32 m0, s65, 0x10000
	ds_read_b128 v[198:201], v173 offset:16384
	ds_read_b128 v[202:205], v173 offset:17408
	ds_read_b128 v[206:209], v173 offset:18432
	ds_read_b128 v[210:213], v173 offset:19456
	ds_read_b128 v[214:217], v173 offset:20480
	ds_read_b128 v[218:221], v173 offset:21504
	ds_read_b128 v[222:225], v173 offset:22528
	ds_read_b128 v[226:229], v173 offset:23552
	global_load_lds_dwordx4 v128, s[46:47]
	s_add_i32 m0, s65, 0x12000
	s_nop 0
	global_load_lds_dwordx4 v136, s[46:47]
	s_add_i32 m0, s65, 0x14000
	s_nop 0
	global_load_lds_dwordx4 v230, s[46:47]
	s_add_i32 m0, s65, 0x16000
	s_nop 0
	global_load_lds_dwordx4 v231, s[46:47]
	s_mov_b32 m0, s68
	s_nop 0
	global_load_lds_dwordx4 v132, s[8:9]
	s_mov_b32 m0, s87
	s_nop 0
	global_load_lds_dwordx4 v134, s[8:9]
	s_waitcnt vmcnt(8)
	s_waitcnt lgkmcnt(0)
	s_barrier
	s_setprio 1
	v_mfma_f32_16x16x32_bf16 v[60:63], v[142:145], v[198:201], v[60:63]
	v_mfma_f32_16x16x32_bf16 v[56:59], v[174:177], v[198:201], v[56:59]
	v_mfma_f32_16x16x32_bf16 v[44:47], v[142:145], v[206:209], v[44:47]
	v_mfma_f32_16x16x32_bf16 v[40:43], v[174:177], v[206:209], v[40:43]
	v_mfma_f32_16x16x32_bf16 v[28:31], v[142:145], v[214:217], v[28:31]
	v_mfma_f32_16x16x32_bf16 v[24:27], v[174:177], v[214:217], v[24:27]
	v_mfma_f32_16x16x32_bf16 v[12:15], v[142:145], v[222:225], v[12:15]
	v_mfma_f32_16x16x32_bf16 v[8:11], v[174:177], v[222:225], v[8:11]
	v_mfma_f32_16x16x32_bf16 v[60:63], v[146:149], v[202:205], v[60:63]
	v_mfma_f32_16x16x32_bf16 v[56:59], v[178:181], v[202:205], v[56:59]
	v_mfma_f32_16x16x32_bf16 v[44:47], v[146:149], v[210:213], v[44:47]
	v_mfma_f32_16x16x32_bf16 v[40:43], v[178:181], v[210:213], v[40:43]
	v_mfma_f32_16x16x32_bf16 v[28:31], v[146:149], v[218:221], v[28:31]
	v_mfma_f32_16x16x32_bf16 v[24:27], v[178:181], v[218:221], v[24:27]
	v_mfma_f32_16x16x32_bf16 v[12:15], v[146:149], v[226:229], v[12:15]
	v_mfma_f32_16x16x32_bf16 v[8:11], v[178:181], v[226:229], v[8:11]
	s_setprio 0
	s_setprio 1
	v_mfma_f32_16x16x32_bf16 v[52:55], v[182:185], v[198:201], v[52:55]
	v_mfma_f32_16x16x32_bf16 v[48:51], v[190:193], v[198:201], v[48:51]
	v_mfma_f32_16x16x32_bf16 v[36:39], v[182:185], v[206:209], v[36:39]
	v_mfma_f32_16x16x32_bf16 v[32:35], v[190:193], v[206:209], v[32:35]
	v_mfma_f32_16x16x32_bf16 v[20:23], v[182:185], v[214:217], v[20:23]
	v_mfma_f32_16x16x32_bf16 v[16:19], v[190:193], v[214:217], v[16:19]
	v_mfma_f32_16x16x32_bf16 v[4:7], v[182:185], v[222:225], v[4:7]
	v_mfma_f32_16x16x32_bf16 v[0:3], v[190:193], v[222:225], v[0:3]
	v_mfma_f32_16x16x32_bf16 v[52:55], v[186:189], v[202:205], v[52:55]
	v_mfma_f32_16x16x32_bf16 v[48:51], v[194:197], v[202:205], v[48:51]
	v_mfma_f32_16x16x32_bf16 v[36:39], v[186:189], v[210:213], v[36:39]
	v_mfma_f32_16x16x32_bf16 v[32:35], v[194:197], v[210:213], v[32:35]
	v_mfma_f32_16x16x32_bf16 v[20:23], v[186:189], v[218:221], v[20:23]
	v_mfma_f32_16x16x32_bf16 v[16:19], v[194:197], v[218:221], v[16:19]
	v_mfma_f32_16x16x32_bf16 v[4:7], v[186:189], v[226:229], v[4:7]
	v_mfma_f32_16x16x32_bf16 v[0:3], v[194:197], v[226:229], v[0:3]
	s_setprio 0
	s_barrier
; #define PG8_STAGE(bufoff, gbase, voff) do { _Pragma("unroll") for (int _i = 0; _i < 2; ++_i) \
;         __builtin_amdgcn_global_load_lds((const unsigned*)((const char*)(gbase) + (voff)[_i]), (PG8_LAS unsigned*)(lds + (bufoff) + ldsw + _i * 8192), 16, 0, 0); } while (0)
; #define PG8_LDA(dst, b, h) do { _Pragma("unroll") for (int m = 0; m < 4; ++m) _Pragma("unroll") for (int k = 0; k < 2; ++k) dst[m][k] = *(const PG8_LAS bf16x8*)(lds + PG8_SA(b, h) + aoff + m * 2048 + k * 1024); } while (0)
; #define PG8_LDB(dst, b, h) do { _Pragma("unroll") for (int n = 0; n < 2; ++n) _Pragma("unroll") for (int k = 0; k < 2; ++k) dst[n][k] = *(const PG8_LAS bf16x8*)(lds + PG8_SB(b, h) + boff + n * 2048 + k * 1024); } while (0)
; #define PG8_MMA(ai, bj, At, Bt) do { __builtin_amdgcn_s_setprio(1); _Pragma("unroll") for (int m = 0; m < 4; ++m) _Pragma("unroll") for (int n = 0; n < 2; ++n) _Pragma("unroll") for (int k = 0; k < 2; ++k) \
;         acc[ai][bj][m][n] = __builtin_amdgcn_mfma_f32_16x16x32_bf16(Bt[n][k], At[m][k], acc[ai][bj][m][n], 0, 0, 0); __builtin_amdgcn_s_setprio(0); } while (0)
; #define PG8_WAIT_V(n) asm volatile("s_waitcnt vmcnt(" #n ")" ::: "memory")
; #define PG8_WAIT_L(n) asm volatile("s_waitcnt lgkmcnt(" #n ")" ::: "memory")
; #define PG8_BAR __builtin_amdgcn_s_barrier()
; #define PG8_SCHED __builtin_amdgcn_sched_barrier(0)
; template <class Epi, class Sched, bool ALIGN_EPI = false, bool SP2 = false>
; __device__ __forceinline__ void gemm_phase(PG8_LAS unsigned char* lds, const Gemm g, const Sched& S, const Epi& E) {
;     ...
;             PG8_LDB(B0, 1, 0); PG8_LDB(B1, 1, 1); PG8_SCHED; PG8_LDA(At, 1, 0); PG8_STAGE(PG8_SA(0, 1), a2 + hstep, voffA);
;             PG8_WAIT_V(8); PG8_WAIT_L(0); PG8_BAR; PG8_MMA(0, 0, At, B0); PG8_MMA(0, 1, At, B1); PG8_BAR; PG8_SCHED;
	ds_read_b128 v[142:145], v232 offset:32768
	ds_read_b128 v[146:149], v232 offset:33792
	ds_read_b128 v[174:177], v232 offset:34816
	ds_read_b128 v[178:181], v232 offset:35840
	ds_read_b128 v[182:185], v232 offset:49152
	ds_read_b128 v[186:189], v232 offset:50176
	ds_read_b128 v[190:193], v232 offset:51200
	ds_read_b128 v[194:197], v232 offset:52224
	s_mov_b32 m0, s1
	ds_read_b128 v[198:201], v173 offset:32768
	ds_read_b128 v[202:205], v173 offset:33792
	ds_read_b128 v[206:209], v173 offset:34816
	ds_read_b128 v[210:213], v173 offset:35840
	ds_read_b128 v[214:217], v173 offset:36864
	ds_read_b128 v[218:221], v173 offset:37888
	ds_read_b128 v[222:225], v173 offset:38912
	ds_read_b128 v[226:229], v173 offset:39936
	global_load_lds_dwordx4 v140, s[8:9]
	s_mov_b32 m0, s0
	s_nop 0
	global_load_lds_dwordx4 v138, s[8:9]
	s_waitcnt vmcnt(8)
	s_waitcnt lgkmcnt(0)
	s_barrier
	s_setprio 1
	v_mfma_f32_16x16x32_bf16 v[124:127], v[142:145], v[198:201], v[124:127]
	v_mfma_f32_16x16x32_bf16 v[120:123], v[174:177], v[198:201], v[120:123]
	v_mfma_f32_16x16x32_bf16 v[108:111], v[142:145], v[206:209], v[108:111]
	v_mfma_f32_16x16x32_bf16 v[104:107], v[174:177], v[206:209], v[104:107]
	v_mfma_f32_16x16x32_bf16 v[92:95], v[142:145], v[214:217], v[92:95]
	v_mfma_f32_16x16x32_bf16 v[88:91], v[174:177], v[214:217], v[88:91]
	v_mfma_f32_16x16x32_bf16 v[76:79], v[142:145], v[222:225], v[76:79]
	v_mfma_f32_16x16x32_bf16 v[72:75], v[174:177], v[222:225], v[72:75]
	v_mfma_f32_16x16x32_bf16 v[124:127], v[146:149], v[202:205], v[124:127]
	v_mfma_f32_16x16x32_bf16 v[120:123], v[178:181], v[202:205], v[120:123]
	v_mfma_f32_16x16x32_bf16 v[108:111], v[146:149], v[210:213], v[108:111]
	v_mfma_f32_16x16x32_bf16 v[104:107], v[178:181], v[210:213], v[104:107]
	v_mfma_f32_16x16x32_bf16 v[92:95], v[146:149], v[218:221], v[92:95]
	v_mfma_f32_16x16x32_bf16 v[88:91], v[178:181], v[218:221], v[88:91]
	v_mfma_f32_16x16x32_bf16 v[76:79], v[146:149], v[226:229], v[76:79]
	v_mfma_f32_16x16x32_bf16 v[72:75], v[178:181], v[226:229], v[72:75]
	s_setprio 0
	s_setprio 1
	v_mfma_f32_16x16x32_bf16 v[116:119], v[182:185], v[198:201], v[116:119]
	v_mfma_f32_16x16x32_bf16 v[112:115], v[190:193], v[198:201], v[112:115]
	v_mfma_f32_16x16x32_bf16 v[100:103], v[182:185], v[206:209], v[100:103]
	v_mfma_f32_16x16x32_bf16 v[96:99], v[190:193], v[206:209], v[96:99]
	v_mfma_f32_16x16x32_bf16 v[84:87], v[182:185], v[214:217], v[84:87]
	v_mfma_f32_16x16x32_bf16 v[80:83], v[190:193], v[214:217], v[80:83]
	v_mfma_f32_16x16x32_bf16 v[68:71], v[182:185], v[222:225], v[68:71]
	v_mfma_f32_16x16x32_bf16 v[64:67], v[190:193], v[222:225], v[64:67]
	v_mfma_f32_16x16x32_bf16 v[116:119], v[186:189], v[202:205], v[116:119]
	v_mfma_f32_16x16x32_bf16 v[112:115], v[194:197], v[202:205], v[112:115]
	v_mfma_f32_16x16x32_bf16 v[100:103], v[186:189], v[210:213], v[100:103]
	v_mfma_f32_16x16x32_bf16 v[96:99], v[194:197], v[210:213], v[96:99]
	v_mfma_f32_16x16x32_bf16 v[84:87], v[186:189], v[218:221], v[84:87]
	v_mfma_f32_16x16x32_bf16 v[80:83], v[194:197], v[218:221], v[80:83]
	v_mfma_f32_16x16x32_bf16 v[68:71], v[186:189], v[226:229], v[68:71]
	v_mfma_f32_16x16x32_bf16 v[64:67], v[194:197], v[226:229], v[64:67]
	s_setprio 0
	s_barrier
; #define PG8_STAGE(bufoff, gbase, voff) do { _Pragma("unroll") for (int _i = 0; _i < 2; ++_i) \
;         __builtin_amdgcn_global_load_lds((const unsigned*)((const char*)(gbase) + (voff)[_i]), (PG8_LAS unsigned*)(lds + (bufoff) + ldsw + _i * 8192), 16, 0, 0); } while (0)
; #define PG8_LDA(dst, b, h) do { _Pragma("unroll") for (int m = 0; m < 4; ++m) _Pragma("unroll") for (int k = 0; k < 2; ++k) dst[m][k] = *(const PG8_LAS bf16x8*)(lds + PG8_SA(b, h) + aoff + m * 2048 + k * 1024); } while (0)
; #define PG8_MMA(ai, bj, At, Bt) do { __builtin_amdgcn_s_setprio(1); _Pragma("unroll") for (int m = 0; m < 4; ++m) _Pragma("unroll") for (int n = 0; n < 2; ++n) _Pragma("unroll") for (int k = 0; k < 2; ++k) \
;         acc[ai][bj][m][n] = __builtin_amdgcn_mfma_f32_16x16x32_bf16(Bt[n][k], At[m][k], acc[ai][bj][m][n], 0, 0, 0); __builtin_amdgcn_s_setprio(0); } while (0)
; #define PG8_WAIT_V(n) asm volatile("s_waitcnt vmcnt(" #n ")" ::: "memory")
; #define PG8_WAIT_L(n) asm volatile("s_waitcnt lgkmcnt(" #n ")" ::: "memory")
; #define PG8_BAR __builtin_amdgcn_s_barrier()
; #define PG8_SCHED __builtin_amdgcn_sched_barrier(0)
;     __device__ __forceinline__ void operator()(const f32x4 (&acc)[2][2][4][2], const Unit& u, int wr, int wc, int fr, int fq) const {
;         const int row0 = u.pm * BM + wr * 64 + fr; const int col0 = u.pn * BM + wc * 32 + 8 * fq;
; #pragma unroll
;         for (int ai = 0; ai < 2; ++ai)
; #pragma unroll
;             for (int m = 0; m < 4; ++m) { const int row = row0 + ai * HALF + m * 16; bf16_t* rowp = O + (size_t)row * ldc + col0;
;                 const float sc = rs ? rs[row] : 1.0f;
; template <class Epi, class Sched, bool ALIGN_EPI = false, bool SP2 = false>
; __device__ __forceinline__ void gemm_phase(PG8_LAS unsigned char* lds, const Gemm g, const Sched& S, const Epi& E) {
;     ...
;             PG8_LDA(At, 1, 1); PG8_STAGE(PG8_SB(1, 0), b3, voffB); PG8_STAGE(PG8_SB(1, 1), b3 + hstep, voffB); PG8_STAGE(PG8_SA(1, 0), a3, voffA);
;             PG8_WAIT_V(8); PG8_WAIT_L(0); PG8_BAR; PG8_MMA(1, 0, At, B0); PG8_MMA(1, 1, At, B1); PG8_BAR; PG8_SCHED;
	s_add_i32 m0, s65, 0x17f80
	ds_read_b128 v[198:201], v173 offset:49152
	ds_read_b128 v[202:205], v173 offset:50176
	ds_read_b128 v[206:209], v173 offset:51200
	ds_read_b128 v[210:213], v173 offset:52224
	ds_read_b128 v[214:217], v173 offset:53248
	ds_read_b128 v[218:221], v173 offset:54272
	ds_read_b128 v[222:225], v173 offset:55296
	ds_read_b128 v[226:229], v173 offset:56320
	global_load_lds_dwordx4 v128, s[46:47] offset:128
	s_add_i32 m0, s65, 0x19f80
	s_nop 0
	global_load_lds_dwordx4 v136, s[46:47] offset:128
	s_add_i32 m0, s65, 0x1bf80
	s_nop 0
	global_load_lds_dwordx4 v230, s[46:47] offset:128
	s_add_i32 m0, s65, 0x1df80
	s_nop 0
	global_load_lds_dwordx4 v231, s[46:47] offset:128
	s_add_i32 m0, s88, 0xffffff80
	s_nop 0
	global_load_lds_dwordx4 v132, s[8:9] offset:128
	s_add_i32 m0, s95, 0xffffff80
	s_nop 0
	global_load_lds_dwordx4 v134, s[8:9] offset:128
	s_waitcnt vmcnt(8)
	s_waitcnt lgkmcnt(0)
	s_barrier
	s_setprio 1
	v_mfma_f32_16x16x32_bf16 v[60:63], v[142:145], v[198:201], v[60:63]
	v_mfma_f32_16x16x32_bf16 v[56:59], v[174:177], v[198:201], v[56:59]
	v_mfma_f32_16x16x32_bf16 v[44:47], v[142:145], v[206:209], v[44:47]
	v_mfma_f32_16x16x32_bf16 v[40:43], v[174:177], v[206:209], v[40:43]
	v_mfma_f32_16x16x32_bf16 v[28:31], v[142:145], v[214:217], v[28:31]
	v_mfma_f32_16x16x32_bf16 v[24:27], v[174:177], v[214:217], v[24:27]
	v_mfma_f32_16x16x32_bf16 v[12:15], v[142:145], v[222:225], v[12:15]
	v_mfma_f32_16x16x32_bf16 v[8:11], v[174:177], v[222:225], v[8:11]
	v_mfma_f32_16x16x32_bf16 v[60:63], v[146:149], v[202:205], v[60:63]
	v_mfma_f32_16x16x32_bf16 v[56:59], v[178:181], v[202:205], v[56:59]
	v_mfma_f32_16x16x32_bf16 v[44:47], v[146:149], v[210:213], v[44:47]
	v_mfma_f32_16x16x32_bf16 v[40:43], v[178:181], v[210:213], v[40:43]
	v_mfma_f32_16x16x32_bf16 v[28:31], v[146:149], v[218:221], v[28:31]
	v_mfma_f32_16x16x32_bf16 v[24:27], v[178:181], v[218:221], v[24:27]
	v_mfma_f32_16x16x32_bf16 v[12:15], v[146:149], v[226:229], v[12:15]
	v_mfma_f32_16x16x32_bf16 v[8:11], v[178:181], v[226:229], v[8:11]
	s_setprio 0
	s_setprio 1
	v_mfma_f32_16x16x32_bf16 v[52:55], v[182:185], v[198:201], v[52:55]
	v_mfma_f32_16x16x32_bf16 v[48:51], v[190:193], v[198:201], v[48:51]
	v_mfma_f32_16x16x32_bf16 v[36:39], v[182:185], v[206:209], v[36:39]
	v_mfma_f32_16x16x32_bf16 v[32:35], v[190:193], v[206:209], v[32:35]
	v_mfma_f32_16x16x32_bf16 v[20:23], v[182:185], v[214:217], v[20:23]
	v_mfma_f32_16x16x32_bf16 v[16:19], v[190:193], v[214:217], v[16:19]
	v_mfma_f32_16x16x32_bf16 v[4:7], v[182:185], v[222:225], v[4:7]
	v_mfma_f32_16x16x32_bf16 v[0:3], v[190:193], v[222:225], v[0:3]
	v_mfma_f32_16x16x32_bf16 v[52:55], v[186:189], v[202:205], v[52:55]
	v_mfma_f32_16x16x32_bf16 v[48:51], v[194:197], v[202:205], v[48:51]
	v_mfma_f32_16x16x32_bf16 v[36:39], v[186:189], v[210:213], v[36:39]
	v_mfma_f32_16x16x32_bf16 v[32:35], v[194:197], v[210:213], v[32:35]
	v_mfma_f32_16x16x32_bf16 v[20:23], v[186:189], v[218:221], v[20:23]
	v_mfma_f32_16x16x32_bf16 v[16:19], v[194:197], v[218:221], v[16:19]
	v_mfma_f32_16x16x32_bf16 v[4:7], v[186:189], v[226:229], v[4:7]
	v_mfma_f32_16x16x32_bf16 v[0:3], v[194:197], v[226:229], v[0:3]
	s_setprio 0
	s_barrier
	s_add_u32 vcc_lo, vcc_lo, 0x100
	s_addc_u32 vcc_hi, vcc_hi, 0
	s_add_u32 s6, s6, 0x100
	s_addc_u32 s7, s7, 0
	s_cmp_ge_u32 s82, s97
	s_mov_b32 s8, s82
	s_cbranch_scc0 .LBB0_300
	v_lshl_add_u32 v142, s71, 8, v131
	v_mov_b32_e32 v143, 0
	v_lshl_or_b32 v191, s91, 8, v172
	s_lshl_b32 s46, s60, 5
	v_mul_lo_u32 v190, v142, s60
	s_mul_i32 s47, s46, 5
	s_andn2_b64 vcc, exec, s[76:77]
	v_add_lshl_u32 v190, v190, v191, 1
	s_cbranch_vccnz .Lepi_nors
	v_lshl_add_u64 v[144:145], v[142:143], 2, s[36:37]
	global_load_dword v174, v[144:145], off
	global_load_dword v176, v[144:145], off offset:64
	global_load_dword v178, v[144:145], off offset:128
	global_load_dword v180, v[144:145], off offset:192
	global_load_dword v182, v[144:145], off offset:512
	global_load_dword v184, v[144:145], off offset:576
	global_load_dword v186, v[144:145], off offset:640
	global_load_dword v188, v[144:145], off offset:704
	s_branch .Lepi_bar
